# ml_local K/V loads and conv: thread mapping (tid>>2, tid&3) so a wave-level load touches 16 rows x 64 B instead of 64 rows x 16 B
# speedup vs baseline: 1.0272x; 1.0146x over previous
; __device__ __forceinline__ void ml_prep_load(const float* G, int b, int n, int h, int tid, float* g4) {
;   const bool isctx = n < 2;
;   const int p0 = isctx ? n * 128 : (n - 2) * 128;
;   const float* g = G + (size_t)ml_row_pos(b, isctx, p0 + (tid & 127)) * 16;
;   g4[0] = g[0 + h]; g4[1] = g[4 + h]; g4[2] = g[8 + h]; g4[3] = g[12 + h];
; }
; __device__ void ml_local_tile(unsigned char* lds, const Params& p, int l, int b, int h, int n) {
;     ...
;   float g4[4];
;   ml_prep_load(G, b, n, h, tid, g4);
;   uint4 ku[4][4], vu[4];
;   {
;     const int s = tid & 127, ec0 = tid >> 7;
;     const int row = ml_row_pos(b, isctx, p0 + s);
; #pragma unroll
;     for (int i = 0; i < 4; ++i) {
;       const int ec = ec0 + 4 * i;
;       ml_conv8_load(z, 768 + 512 + h * 128 + ec * 8, b, isctx, L, p0 + s, ku[i]);
;       vu[i] = *(const uint4*)(z + (size_t)row * ZS + 768 + 1024 + h * 128 + ec * 8);
;     }
.LBB0_336:
	v_ashrrev_i32_e32 v1, 31, v0
	v_readlane_b32 s2, v251, 0
	s_and_b32 s25, s21, 3
	v_lshlrev_b64 v[0:1], 6, v[0:1]
	v_readlane_b32 s3, v251, 1
	s_lshl_b32 s96, s25, 2
	s_and_b64 vcc, exec, s[0:1]
	v_lshl_add_u64 v[0:1], s[2:3], 0, v[0:1]
	v_lshl_add_u64 v[0:1], v[0:1], 0, s[96:97]
	global_load_dword v89, v[0:1], off
	global_load_dword v90, v[0:1], off offset:16
	global_load_dword v80, v[0:1], off offset:32
	global_load_dword v81, v[0:1], off offset:48
	v_lshrrev_b32_e32 v108, 2, v88
	v_and_b32_e32 v109, 3, v88
	v_or_b32_e32 v92, s4, v108
	v_lshlrev_b32_e32 v4, 6, v92
	v_and_b32_e32 v4, 0x7c0, v4
	v_ashrrev_i32_e32 v3, 5, v92
	s_mov_b64 s[2:3], -1
	s_cbranch_vccz .LBB0_338
	s_lshl_b32 s1, s5, 8
	s_lshl_b32 s0, s5, 11
	s_addk_i32 s1, 0x4000
	v_add3_u32 v2, v3, s0, v4
	s_mov_b64 s[2:3], 0
	v_mov_b32_e32 v0, s1
	v_mov_b32_e32 v1, s0

; __device__ __forceinline__ int opaque_tid() { int t = threadIdx.x; asm volatile("" : "+v"(t)); return t; }
; __device__ __forceinline__ float logsig(float x) { return fminf(x, 0.f) - __logf(1.f + fexp(-fabsf(x))); }
; __device__ __forceinline__ void ml_prep(float* vec, const float* g4, float* scal, int b, int n, int h, bool outmode) {
;   const int tid = opaque_tid();
;   if (tid < 128) {
;     vec[0 * 128 + tid] = g4[0];
;     vec[1 * 128 + tid] = logsig(g4[1]);
;     vec[2 * 128 + tid] = g4[2];
;     vec[3 * 128 + tid] = logsig(g4[3]);
;   }
; __device__ void ml_local_tile(unsigned char* lds, const Params& p, int l, int b, int h, int n) {
;     ...
;   uint4 ku[4][4], vu[4];
;   {
;     const int s = tid & 127, ec0 = tid >> 7;
;     const int row = ml_row_pos(b, isctx, p0 + s);
; #pragma unroll
;     for (int i = 0; i < 4; ++i) {
;       const int ec = ec0 + 4 * i;
;       ml_conv8_load(z, 768 + 512 + h * 128 + ec * 8, b, isctx, L, p0 + s, ku[i]);
;       vu[i] = *(const uint4*)(z + (size_t)row * ZS + 768 + 1024 + h * 128 + ec * 8);
;     }
;   }
.LBB0_340:
	s_and_b64 s[0:1], s[6:7], exec
	s_movk_i32 s0, 0x800
	s_cselect_b32 s26, 0x100, s0
	v_min_u32_e32 v3, s26, v92
	s_lshl_b32 s96, s25, 7
	v_add_u32_e32 v3, -1, v3
	v_cmp_lt_i32_e64 s[0:1], 0, v92
	s_add_i32 s8, s96, 0x500
	s_cmp_gt_i32 s4, -1
	v_cndmask_b32_e64 v6, 0, v3, s[0:1]
	v_add_u32_e32 v3, 1, v92
	v_min_u32_e32 v3, s26, v3
	v_add_u32_e32 v3, -1, v3
	s_cselect_b64 vcc, -1, 0
	v_add_u32_e32 v93, 2, v92
	v_cndmask_b32_e32 v7, 0, v3, vcc
	v_min_u32_e32 v3, s26, v93
	v_add_u32_e32 v3, -1, v3
	v_cmp_lt_i32_e64 s[2:3], -2, v92
	v_add_u32_e32 v97, 3, v92
	v_cmp_lt_i32_e64 s[4:5], -3, v92
	v_cndmask_b32_e64 v8, 0, v3, s[2:3]
	v_min_u32_e32 v3, s26, v97
	v_add_u32_e32 v3, -1, v3
	v_mov_b64_e32 v[4:5], s[88:89]
	v_cndmask_b32_e64 v9, 0, v3, s[4:5]
	v_mad_i64_i32 v[2:3], s[22:23], v2, s92, v[4:5]
	v_lshlrev_b32_e32 v4, 6, v6
	v_and_b32_e32 v4, 0x7c0, v4
	v_ashrrev_i32_e32 v5, 5, v6
	v_add3_u32 v4, v4, v5, v1
	v_add_u32_e32 v5, v0, v6
	v_lshlrev_b32_e32 v6, 6, v7
	v_and_b32_e32 v6, 0x7c0, v6
	v_ashrrev_i32_e32 v10, 5, v7
	v_ashrrev_i32_e32 v87, 7, v88
	v_add3_u32 v6, v6, v10, v1
	v_lshlrev_b32_e32 v10, 6, v8
	v_lshlrev_b32_e32 v82, 3, v109
	v_and_b32_e32 v10, 0x7c0, v10
	v_ashrrev_i32_e32 v11, 5, v8
	v_add3_u32 v10, v10, v11, v1
	v_lshlrev_b32_e32 v11, 6, v9
	v_ashrrev_i32_e32 v83, 31, v82
	v_and_b32_e32 v11, 0x7c0, v11
	v_ashrrev_i32_e32 v12, 5, v9
	v_lshl_add_u64 v[84:85], v[82:83], 0, s[96:97]
	s_lshl_b32 s22, s25, 8
	s_mov_b32 s23, s97
	v_add_u32_e32 v7, v0, v7
	v_add_u32_e32 v8, v0, v8
	v_add3_u32 v11, v11, v12, v1
	v_add_u32_e32 v9, v0, v9
	v_lshl_add_u64 v[0:1], v[84:85], 1, s[88:89]
	v_cndmask_b32_e64 v12, v4, v5, s[6:7]
	v_lshl_add_u64 v[2:3], v[2:3], 0, s[22:23]
	v_mad_i64_i32 v[4:5], s[22:23], v12, s92, v[0:1]
	v_cndmask_b32_e64 v13, v6, v7, s[6:7]
	v_cndmask_b32_e64 v8, v10, v8, s[6:7]
	v_cndmask_b32_e64 v10, v11, v9, s[6:7]
	v_mad_i64_i32 v[6:7], s[22:23], v13, s92, v[0:1]
	global_load_dwordx4 v[76:79], v[4:5], off offset:2560
	global_load_dwordx4 v[72:75], v[6:7], off offset:2560
	v_mad_i64_i32 v[4:5], s[22:23], v8, s92, v[0:1]
	v_mad_i64_i32 v[0:1], s[6:7], v10, s92, v[0:1]
	s_mov_b32 s9, s97
	global_load_dwordx4 v[68:71], v[4:5], off offset:2560
	global_load_dwordx4 v[64:67], v[0:1], off offset:2560
	v_lshl_add_u64 v[0:1], v[82:83], 1, v[2:3]
	v_lshl_add_u64 v[2:3], v[82:83], 0, s[8:9]
	v_lshl_add_u64 v[2:3], v[2:3], 1, s[88:89]
	v_mad_i64_i32 v[4:5], s[6:7], v12, s92, v[2:3]
	v_mad_i64_i32 v[6:7], s[6:7], v13, s92, v[2:3]
	v_mad_i64_i32 v[8:9], s[6:7], v8, s92, v[2:3]
	v_mad_i64_i32 v[2:3], s[6:7], v10, s92, v[2:3]
	global_load_dwordx4 v[60:63], v[0:1], off offset:3584
	global_load_dwordx4 v[40:43], v[0:1], off offset:3648
	global_load_dwordx4 v[56:59], v[4:5], off offset:64
	global_load_dwordx4 v[36:39], v[4:5], off offset:128
	global_load_dwordx4 v[48:51], v[8:9], off offset:64
	global_load_dwordx4 v[28:31], v[8:9], off offset:128
	global_load_dwordx4 v[52:55], v[6:7], off offset:64
	global_load_dwordx4 v[16:19], v[4:5], off offset:192
	global_load_dwordx4 v[32:35], v[6:7], off offset:128
	global_load_dwordx4 v[12:15], v[6:7], off offset:192
	global_load_dwordx4 v[44:47], v[2:3], off offset:64
	s_nop 0
	global_load_dwordx4 v[8:11], v[8:9], off offset:192
	s_nop 0
	global_load_dwordx4 v[24:27], v[2:3], off offset:128
	global_load_dwordx4 v[4:7], v[2:3], off offset:192
	global_load_dwordx4 v[20:23], v[0:1], off offset:3712
	s_nop 0
	global_load_dwordx4 v[0:3], v[0:1], off offset:3776
	v_mov_b32_e32 v91, v195
	s_nop 0
	v_cmp_gt_i32_e32 vcc, s91, v91
	s_and_saveexec_b64 s[22:23], vcc
	s_cbranch_execz .LBB0_342
	s_mov_b32 s29, 0xbfb8aa3b
	s_waitcnt vmcnt(22)
	v_max_f32_e32 v95, v90, v90
	v_mul_f32_e64 v90, |v90|, s29
	v_exp_f32_e32 v90, v90
	s_mov_b32 s27, 0x800000
	s_mov_b32 s30, 0x3f317217
	s_mov_b32 s28, 0x7f800000
	v_add_f32_e32 v90, 1.0, v90
	v_cmp_gt_f32_e64 s[6:7], s27, v90
	v_mov_b32_e32 v98, 0x41b17218
	v_lshl_add_u32 v94, v91, 2, 0
	v_cndmask_b32_e64 v96, 0, 32, s[6:7]
	v_ldexp_f32 v90, v90, v96
	v_log_f32_e32 v90, v90
	v_min_f32_e32 v95, 0, v95
	v_add_u32_e32 v94, 0x19800, v94
	v_mul_f32_e32 v96, 0x3f317217, v90
	v_fma_f32 v96, v90, s30, -v96
	v_fmac_f32_e32 v96, 0x3377d1cf, v90
	v_fmac_f32_e32 v96, 0x3f317217, v90
	v_cmp_lt_f32_e64 s[8:9], |v90|, s28
	s_nop 1
	v_cndmask_b32_e64 v90, v90, v96, s[8:9]
	v_cndmask_b32_e64 v96, 0, v98, s[6:7]
	v_sub_f32_e32 v90, v90, v96
	v_sub_f32_e32 v90, v95, v90
	ds_write2st64_b32 v94, v89, v90 offset1:2
	s_waitcnt vmcnt(20)
	v_max_f32_e32 v89, v81, v81
	v_mul_f32_e64 v81, |v81|, s29
	v_exp_f32_e32 v81, v81
	v_min_f32_e32 v89, 0, v89
	v_add_f32_e32 v81, 1.0, v81
	v_cmp_gt_f32_e64 s[6:7], s27, v81
	s_nop 1
	v_cndmask_b32_e64 v90, 0, 32, s[6:7]
	v_ldexp_f32 v81, v81, v90
	v_log_f32_e32 v81, v81
	s_nop 0
	v_mul_f32_e32 v90, 0x3f317217, v81
	v_fma_f32 v90, v81, s30, -v90
	v_fmac_f32_e32 v90, 0x3377d1cf, v81
	v_fmac_f32_e32 v90, 0x3f317217, v81
	v_cmp_lt_f32_e64 s[8:9], |v81|, s28
	s_nop 1
	v_cndmask_b32_e64 v81, v81, v90, s[8:9]
	v_cndmask_b32_e64 v90, 0, v98, s[6:7]
	v_sub_f32_e32 v81, v81, v90
	v_sub_f32_e32 v81, v89, v81
	ds_write2st64_b32 v94, v80, v81 offset0:4 offset1:6

; __device__ __forceinline__ bf16_t f2bf(float f) { return (bf16_t)(pack2(f, 0.f) & 0xffffu); }
; __device__ __forceinline__ void ml_conv8_comp(const uint4* u, const float* wc, int ccol, int L, int pos, float* o) {
; #pragma unroll
;   for (int e = 0; e < 8; ++e) o[e] = 0.f;
; #pragma unroll
;   for (int j = 0; j < 4; ++j) {
;     const int pp = pos + j - 1;
;     const float mk = (pp >= 0 && pp < L) ? 1.f : 0.f;
;     float f[8];
;     unpack8(u[j], f);
;     const float4 w0 = *(const float4*)(wc + j * 1024 + ccol);
;     const float4 w1 = *(const float4*)(wc + j * 1024 + ccol + 4);
;     o[0] += f[0] * (w0.x * mk); o[1] += f[1] * (w0.y * mk); o[2] += f[2] * (w0.z * mk); o[3] += f[3] * (w0.w * mk);
;     o[4] += f[4] * (w1.x * mk); o[5] += f[5] * (w1.y * mk); o[6] += f[6] * (w1.z * mk); o[7] += f[7] * (w1.w * mk);
;   }
; __device__ void ml_local_tile(unsigned char* lds, const Params& p, int l, int b, int h, int n) {
;     ...
;   {
;     const int s = tid & 127, ec0 = tid >> 7;
;     const float wf = vec[6 * 128 + s], wb = vec[7 * 128 + s];
;     const float* wc = p.in[18] + (size_t)l * 4 * 1024;
; #pragma unroll
;     for (int i = 0; i < 4; ++i) {
;       const int ec = ec0 + 4 * i;
;       float k8[8];
;       ml_conv8_comp(ku[i], wc, 512 + h * 128 + ec * 8, L, p0 + s, k8);
;       float v8[8];
;       unpack8(vu[i], v8);
; #pragma unroll
;       for (int e = 0; e < 8; ++e) {
;         KT[(ec * 8 + e) * 136 + s] = f2bf(k8[e] * 0.08838834764831845f);
.LBB0_345:
	s_or_b64 exec, exec, s[8:9]
	s_movk_i32 s6, 0x88
	v_cmp_ge_i32_e32 vcc, s26, v92
	v_mul_lo_u32 v96, v82, s6
	s_add_i32 s6, 0, 0x19800
	s_and_b64 s[0:1], s[0:1], vcc
	v_cmp_gt_u32_e32 vcc, s26, v92
	s_waitcnt vmcnt(21)
	v_lshl_add_u32 v80, v108, 2, s6
	v_lshl_add_u64 v[84:85], v[84:85], 2, s[18:19]
	v_cndmask_b32_e64 v94, 0, 1.0, vcc
	v_cmp_ge_i32_e32 vcc, s26, v93
	s_waitcnt lgkmcnt(0)
	s_barrier
	ds_read2st64_b32 v[80:81], v80 offset0:12 offset1:14
	s_bitset1_b32 s96, 9
	v_ashrrev_i32_e32 v89, 6, v88
	v_and_b32_e32 v90, 15, v88
	v_bfe_u32 v91, v88, 4, 2
	v_lshlrev_b32_e32 v192, 3, v91
	v_readlane_b32 s0, v253, 38
	s_mov_b64 s[2:3], 0x1000
	v_lshl_add_u64 v[178:179], v[84:85], 0, s[2:3]
	s_mov_b64 s[2:3], 0x2000
	v_lshl_add_u64 v[180:181], v[84:85], 0, s[2:3]
	s_mov_b64 s[2:3], 0x3000
	v_lshl_add_u64 v[182:183], v[84:85], 0, s[2:3]
	global_load_dwordx4 v[114:117], v[84:85], off offset:2048
	global_load_dwordx4 v[118:121], v[84:85], off offset:2064
	global_load_dwordx4 v[122:125], v[178:179], off offset:2048
	global_load_dwordx4 v[126:129], v[178:179], off offset:2064
	global_load_dwordx4 v[130:133], v[180:181], off offset:2048
	global_load_dwordx4 v[134:137], v[180:181], off offset:2064
	global_load_dwordx4 v[138:141], v[182:183], off offset:2048
	global_load_dwordx4 v[142:145], v[182:183], off offset:2064
	global_load_dwordx4 v[146:149], v[84:85], off offset:2176
	global_load_dwordx4 v[150:153], v[84:85], off offset:2192
	global_load_dwordx4 v[154:157], v[178:179], off offset:2176
	global_load_dwordx4 v[158:161], v[178:179], off offset:2192
	global_load_dwordx4 v[162:165], v[180:181], off offset:2176
	global_load_dwordx4 v[166:169], v[180:181], off offset:2192
	global_load_dwordx4 v[170:173], v[182:183], off offset:2176
	global_load_dwordx4 v[174:177], v[182:183], off offset:2192
	v_add_u32_e32 v93, 1, v92
	v_add_u32_e32 v97, 2, v92
	v_cmp_lt_i32_e64 s[4:5], 0, v92
	v_cmp_gt_i32_e64 s[6:7], s26, v93
	v_cmp_gt_i32_e32 vcc, s26, v97
	s_movk_i32 s1, 0x440
	v_mul_lo_u32 v106, v109, s1
	v_mov_b32_e32 v94, 1.0
	v_cndmask_b32_e64 v95, 0, 1.0, s[4:5]
	v_cndmask_b32_e64 v93, 0, 1.0, s[6:7]
	v_cndmask_b32_e64 v92, 0, 1.0, vcc
	v_add_lshl_u32 v106, v106, v108, 1
	v_add_u32_e32 v107, s0, v106
	s_waitcnt vmcnt(8) lgkmcnt(0)
	v_mul_f32_e32 v104, v95, v114
	v_lshlrev_b32_e32 v105, 16, v76
	v_fma_f32 v96, v104, v105, 0
	v_mul_f32_e32 v104, v95, v115
	v_and_b32_e32 v105, 0xffff0000, v76
	v_fma_f32 v97, v104, v105, 0
	v_mul_f32_e32 v104, v95, v116
	v_lshlrev_b32_e32 v105, 16, v77
	v_fma_f32 v98, v104, v105, 0
	v_mul_f32_e32 v104, v95, v117
	v_and_b32_e32 v105, 0xffff0000, v77
	v_fma_f32 v99, v104, v105, 0
	v_mul_f32_e32 v104, v95, v118
	v_lshlrev_b32_e32 v105, 16, v78
	v_fma_f32 v100, v104, v105, 0
	v_mul_f32_e32 v104, v95, v119
	v_and_b32_e32 v105, 0xffff0000, v78
	v_fma_f32 v101, v104, v105, 0
	v_mul_f32_e32 v104, v95, v120
	v_lshlrev_b32_e32 v105, 16, v79
	v_fma_f32 v102, v104, v105, 0
	v_mul_f32_e32 v104, v95, v121
	v_and_b32_e32 v105, 0xffff0000, v79
	v_fma_f32 v103, v104, v105, 0
	v_mul_f32_e32 v104, v94, v122
	v_lshlrev_b32_e32 v105, 16, v72
	v_fmac_f32_e32 v96, v104, v105
	v_mul_f32_e32 v104, v94, v123
	v_and_b32_e32 v105, 0xffff0000, v72
	v_fmac_f32_e32 v97, v104, v105
	v_mul_f32_e32 v104, v94, v124
	v_lshlrev_b32_e32 v105, 16, v73
	v_fmac_f32_e32 v98, v104, v105
	v_mul_f32_e32 v104, v94, v125
	v_and_b32_e32 v105, 0xffff0000, v73
	v_fmac_f32_e32 v99, v104, v105
	v_mul_f32_e32 v104, v94, v126
	v_lshlrev_b32_e32 v105, 16, v74
	v_fmac_f32_e32 v100, v104, v105
	v_mul_f32_e32 v104, v94, v127
	v_and_b32_e32 v105, 0xffff0000, v74
	v_fmac_f32_e32 v101, v104, v105
	v_mul_f32_e32 v104, v94, v128
	v_lshlrev_b32_e32 v105, 16, v75
	v_fmac_f32_e32 v102, v104, v105
	v_mul_f32_e32 v104, v94, v129
	v_and_b32_e32 v105, 0xffff0000, v75
	v_fmac_f32_e32 v103, v104, v105
	v_mul_f32_e32 v104, v93, v130
	v_lshlrev_b32_e32 v105, 16, v68
	v_fmac_f32_e32 v96, v104, v105
	v_mul_f32_e32 v104, v93, v131
	v_and_b32_e32 v105, 0xffff0000, v68
	v_fmac_f32_e32 v97, v104, v105
	v_mul_f32_e32 v104, v93, v132
	v_lshlrev_b32_e32 v105, 16, v69
	v_fmac_f32_e32 v98, v104, v105
	v_mul_f32_e32 v104, v93, v133
	v_and_b32_e32 v105, 0xffff0000, v69
	v_fmac_f32_e32 v99, v104, v105
	v_mul_f32_e32 v104, v93, v134
	v_lshlrev_b32_e32 v105, 16, v70
	v_fmac_f32_e32 v100, v104, v105
	v_mul_f32_e32 v104, v93, v135
	v_and_b32_e32 v105, 0xffff0000, v70
	v_fmac_f32_e32 v101, v104, v105
	v_mul_f32_e32 v104, v93, v136
	v_lshlrev_b32_e32 v105, 16, v71
	v_fmac_f32_e32 v102, v104, v105
	v_mul_f32_e32 v104, v93, v137
	v_and_b32_e32 v105, 0xffff0000, v71
	v_fmac_f32_e32 v103, v104, v105
	v_mul_f32_e32 v104, v92, v138
	v_lshlrev_b32_e32 v105, 16, v64
	v_fmac_f32_e32 v96, v104, v105
	v_mul_f32_e32 v104, v92, v139
	v_and_b32_e32 v105, 0xffff0000, v64
	v_fmac_f32_e32 v97, v104, v105
	v_mul_f32_e32 v104, v92, v140
	v_lshlrev_b32_e32 v105, 16, v65
	v_fmac_f32_e32 v98, v104, v105
	v_mul_f32_e32 v104, v92, v141
	v_and_b32_e32 v105, 0xffff0000, v65
	v_fmac_f32_e32 v99, v104, v105
	v_mul_f32_e32 v104, v92, v142
	v_lshlrev_b32_e32 v105, 16, v66
	v_fmac_f32_e32 v100, v104, v105
	v_mul_f32_e32 v104, v92, v143
	v_and_b32_e32 v105, 0xffff0000, v66
	v_fmac_f32_e32 v101, v104, v105
	v_mul_f32_e32 v104, v92, v144
	v_lshlrev_b32_e32 v105, 16, v67
	v_fmac_f32_e32 v102, v104, v105
	v_mul_f32_e32 v104, v92, v145
	v_and_b32_e32 v105, 0xffff0000, v67
	v_fmac_f32_e32 v103, v104, v105
	v_mul_f32_e32 v184, 0xbfb8aa3b, v96
	v_mul_f32_e32 v185, 0xbfb8aa3b, v97
	v_mul_f32_e32 v186, 0xbfb8aa3b, v98
	v_mul_f32_e32 v187, 0xbfb8aa3b, v99
	v_mul_f32_e32 v188, 0xbfb8aa3b, v100
	v_mul_f32_e32 v189, 0xbfb8aa3b, v101
; __device__ __forceinline__ bf16_t f2bf(float f) { return (bf16_t)(pack2(f, 0.f) & 0xffffu); }
; __device__ void ml_local_tile(unsigned char* lds, const Params& p, int l, int b, int h, int n) {
;     ...
;     const float wf = vec[6 * 128 + s], wb = vec[7 * 128 + s];
;     const float* wc = p.in[18] + (size_t)l * 4 * 1024;
; #pragma unroll
;     for (int i = 0; i < 4; ++i) {
;       const int ec = ec0 + 4 * i;
;       float k8[8];
;       ml_conv8_comp(ku[i], wc, 512 + h * 128 + ec * 8, L, p0 + s, k8);
;       float v8[8];
;       unpack8(vu[i], v8);
; #pragma unroll
;       for (int e = 0; e < 8; ++e) {
;         KT[(ec * 8 + e) * 136 + s] = f2bf(k8[e] * 0.08838834764831845f);
;         VF[(ec * 8 + e) * 136 + s] = f2bf(v8[e] * wf);
;         VB[(ec * 8 + e) * 136 + s] = f2bf(v8[e] * wb);
;       }
;     }
	v_mul_f32_e32 v190, 0xbfb8aa3b, v102
	v_mul_f32_e32 v191, 0xbfb8aa3b, v103
	v_exp_f32_e32 v184, v184
	v_exp_f32_e32 v185, v185
	v_exp_f32_e32 v186, v186
	v_exp_f32_e32 v187, v187
	v_exp_f32_e32 v188, v188
	v_exp_f32_e32 v189, v189
	v_exp_f32_e32 v190, v190
	v_exp_f32_e32 v191, v191
	v_add_f32_e32 v184, 1.0, v184
	v_add_f32_e32 v185, 1.0, v185
	v_add_f32_e32 v186, 1.0, v186
	v_add_f32_e32 v187, 1.0, v187
	v_add_f32_e32 v188, 1.0, v188
	v_add_f32_e32 v189, 1.0, v189
	v_add_f32_e32 v190, 1.0, v190
	v_add_f32_e32 v191, 1.0, v191
	v_rcp_f32_e32 v184, v184
	v_rcp_f32_e32 v185, v185
	v_rcp_f32_e32 v186, v186
	v_rcp_f32_e32 v187, v187
	v_rcp_f32_e32 v188, v188
	v_rcp_f32_e32 v189, v189
	v_rcp_f32_e32 v190, v190
	v_rcp_f32_e32 v191, v191
	s_nop 0
	v_mul_f32_e32 v96, v96, v184
	v_mul_f32_e32 v97, v97, v185
	v_mul_f32_e32 v98, v98, v186
	v_mul_f32_e32 v99, v99, v187
	v_mul_f32_e32 v100, v100, v188
	v_mul_f32_e32 v101, v101, v189
	v_mul_f32_e32 v102, v102, v190
	v_mul_f32_e32 v103, v103, v191
	v_mul_f32_e32 v96, 0x3db504f3, v96
	v_mul_f32_e32 v97, 0x3db504f3, v97
	v_mul_f32_e32 v98, 0x3db504f3, v98
	v_mul_f32_e32 v99, 0x3db504f3, v99
	v_mul_f32_e32 v100, 0x3db504f3, v100
	v_mul_f32_e32 v101, 0x3db504f3, v101
	v_mul_f32_e32 v102, 0x3db504f3, v102
	v_mul_f32_e32 v103, 0x3db504f3, v103
	v_cvt_pk_bf16_f32 v184, v96, v96
	v_cvt_pk_bf16_f32 v185, v97, v97
	v_cvt_pk_bf16_f32 v186, v98, v98
	v_cvt_pk_bf16_f32 v187, v99, v99
	v_cvt_pk_bf16_f32 v188, v100, v100
	v_cvt_pk_bf16_f32 v189, v101, v101
	v_cvt_pk_bf16_f32 v190, v102, v102
	v_cvt_pk_bf16_f32 v191, v103, v103
	ds_write_b16 v106, v184
	ds_write_b16 v106, v185 offset:272
	ds_write_b16 v106, v186 offset:544
	ds_write_b16 v106, v187 offset:816
	ds_write_b16 v106, v188 offset:1088
	ds_write_b16 v106, v189 offset:1360
	ds_write_b16 v106, v190 offset:1632
	ds_write_b16 v106, v191 offset:1904
	v_lshlrev_b32_e32 v105, 16, v60
	v_mul_f32_e32 v104, v80, v105
	v_mul_f32_e32 v112, v81, v105
	v_cvt_pk_bf16_f32 v104, v104, v104
	v_cvt_pk_bf16_f32 v112, v112, v112
	ds_write_b16 v106, v104 offset:34816
	ds_write_b16 v107, v112
	v_and_b32_e32 v105, 0xffff0000, v60
	v_mul_f32_e32 v104, v80, v105
	v_mul_f32_e32 v112, v81, v105
	v_cvt_pk_bf16_f32 v104, v104, v104
	v_cvt_pk_bf16_f32 v112, v112, v112
	ds_write_b16 v106, v104 offset:35088
	ds_write_b16 v107, v112 offset:272
	v_lshlrev_b32_e32 v105, 16, v61
	v_mul_f32_e32 v104, v80, v105
	v_mul_f32_e32 v112, v81, v105
	v_cvt_pk_bf16_f32 v104, v104, v104
	v_cvt_pk_bf16_f32 v112, v112, v112
	ds_write_b16 v106, v104 offset:35360
	ds_write_b16 v107, v112 offset:544
	v_and_b32_e32 v105, 0xffff0000, v61
	v_mul_f32_e32 v104, v80, v105
	v_mul_f32_e32 v112, v81, v105
	v_cvt_pk_bf16_f32 v104, v104, v104
	v_cvt_pk_bf16_f32 v112, v112, v112
	ds_write_b16 v106, v104 offset:35632
	ds_write_b16 v107, v112 offset:816
	v_lshlrev_b32_e32 v105, 16, v62
	v_mul_f32_e32 v104, v80, v105
	v_mul_f32_e32 v112, v81, v105
	v_cvt_pk_bf16_f32 v104, v104, v104
	v_cvt_pk_bf16_f32 v112, v112, v112
	ds_write_b16 v106, v104 offset:35904
	ds_write_b16 v107, v112 offset:1088
	v_and_b32_e32 v105, 0xffff0000, v62
	v_mul_f32_e32 v104, v80, v105
	v_mul_f32_e32 v112, v81, v105
	v_cvt_pk_bf16_f32 v104, v104, v104
	v_cvt_pk_bf16_f32 v112, v112, v112
	ds_write_b16 v106, v104 offset:36176
	ds_write_b16 v107, v112 offset:1360
	v_lshlrev_b32_e32 v105, 16, v63
	v_mul_f32_e32 v104, v80, v105
	v_mul_f32_e32 v112, v81, v105
	v_cvt_pk_bf16_f32 v104, v104, v104
	v_cvt_pk_bf16_f32 v112, v112, v112
	ds_write_b16 v106, v104 offset:36448
	ds_write_b16 v107, v112 offset:1632
	v_and_b32_e32 v105, 0xffff0000, v63
	v_mul_f32_e32 v104, v80, v105
	v_mul_f32_e32 v112, v81, v105
	v_cvt_pk_bf16_f32 v104, v104, v104
	v_cvt_pk_bf16_f32 v112, v112, v112
	ds_write_b16 v106, v104 offset:36720
	ds_write_b16 v107, v112 offset:1904
	global_load_dwordx4 v[114:117], v[84:85], off offset:2304
	global_load_dwordx4 v[118:121], v[84:85], off offset:2320
	global_load_dwordx4 v[122:125], v[178:179], off offset:2304
	global_load_dwordx4 v[126:129], v[178:179], off offset:2320
	global_load_dwordx4 v[130:133], v[180:181], off offset:2304
	global_load_dwordx4 v[134:137], v[180:181], off offset:2320
	global_load_dwordx4 v[138:141], v[182:183], off offset:2304
	global_load_dwordx4 v[142:145], v[182:183], off offset:2320
	s_waitcnt vmcnt(8)
; __device__ __forceinline__ bf16_t f2bf(float f) { return (bf16_t)(pack2(f, 0.f) & 0xffffu); }
; __device__ void ml_local_tile(unsigned char* lds, const Params& p, int l, int b, int h, int n) {
;     ...
;     for (int i = 0; i < 4; ++i) {
;       const int ec = ec0 + 4 * i;
;       float k8[8];
;       ml_conv8_comp(ku[i], wc, 512 + h * 128 + ec * 8, L, p0 + s, k8);
;       float v8[8];
;       unpack8(vu[i], v8);
; #pragma unroll
;       for (int e = 0; e < 8; ++e) {
;         KT[(ec * 8 + e) * 136 + s] = f2bf(k8[e] * 0.08838834764831845f);
;         VF[(ec * 8 + e) * 136 + s] = f2bf(v8[e] * wf);
;         VB[(ec * 8 + e) * 136 + s] = f2bf(v8[e] * wb);
;       }
;     }
	v_mul_f32_e32 v104, v95, v146
	v_lshlrev_b32_e32 v105, 16, v56
	v_fma_f32 v96, v104, v105, 0
	v_mul_f32_e32 v104, v95, v147
	v_and_b32_e32 v105, 0xffff0000, v56
	v_fma_f32 v97, v104, v105, 0
	v_mul_f32_e32 v104, v95, v148
	v_lshlrev_b32_e32 v105, 16, v57
	v_fma_f32 v98, v104, v105, 0
	v_mul_f32_e32 v104, v95, v149
	v_and_b32_e32 v105, 0xffff0000, v57
	v_fma_f32 v99, v104, v105, 0
	v_mul_f32_e32 v104, v95, v150
	v_lshlrev_b32_e32 v105, 16, v58
	v_fma_f32 v100, v104, v105, 0
	v_mul_f32_e32 v104, v95, v151
	v_and_b32_e32 v105, 0xffff0000, v58
	v_fma_f32 v101, v104, v105, 0
	v_mul_f32_e32 v104, v95, v152
	v_lshlrev_b32_e32 v105, 16, v59
	v_fma_f32 v102, v104, v105, 0
	v_mul_f32_e32 v104, v95, v153
	v_and_b32_e32 v105, 0xffff0000, v59
	v_fma_f32 v103, v104, v105, 0
	v_mul_f32_e32 v104, v94, v154
	v_lshlrev_b32_e32 v105, 16, v52
	v_fmac_f32_e32 v96, v104, v105
	v_mul_f32_e32 v104, v94, v155
	v_and_b32_e32 v105, 0xffff0000, v52
	v_fmac_f32_e32 v97, v104, v105
	v_mul_f32_e32 v104, v94, v156
	v_lshlrev_b32_e32 v105, 16, v53
	v_fmac_f32_e32 v98, v104, v105
	v_mul_f32_e32 v104, v94, v157
	v_and_b32_e32 v105, 0xffff0000, v53
	v_fmac_f32_e32 v99, v104, v105
	v_mul_f32_e32 v104, v94, v158
	v_lshlrev_b32_e32 v105, 16, v54
	v_fmac_f32_e32 v100, v104, v105
	v_mul_f32_e32 v104, v94, v159
	v_and_b32_e32 v105, 0xffff0000, v54
	v_fmac_f32_e32 v101, v104, v105
	v_mul_f32_e32 v104, v94, v160
	v_lshlrev_b32_e32 v105, 16, v55
	v_fmac_f32_e32 v102, v104, v105
	v_mul_f32_e32 v104, v94, v161
	v_and_b32_e32 v105, 0xffff0000, v55
	v_fmac_f32_e32 v103, v104, v105
	v_mul_f32_e32 v104, v93, v162
	v_lshlrev_b32_e32 v105, 16, v48
	v_fmac_f32_e32 v96, v104, v105
	v_mul_f32_e32 v104, v93, v163
	v_and_b32_e32 v105, 0xffff0000, v48
	v_fmac_f32_e32 v97, v104, v105
	v_mul_f32_e32 v104, v93, v164
	v_lshlrev_b32_e32 v105, 16, v49
	v_fmac_f32_e32 v98, v104, v105
	v_mul_f32_e32 v104, v93, v165
	v_and_b32_e32 v105, 0xffff0000, v49
	v_fmac_f32_e32 v99, v104, v105
	v_mul_f32_e32 v104, v93, v166
	v_lshlrev_b32_e32 v105, 16, v50
	v_fmac_f32_e32 v100, v104, v105
	v_mul_f32_e32 v104, v93, v167
	v_and_b32_e32 v105, 0xffff0000, v50
	v_fmac_f32_e32 v101, v104, v105
	v_mul_f32_e32 v104, v93, v168
	v_lshlrev_b32_e32 v105, 16, v51
	v_fmac_f32_e32 v102, v104, v105
	v_mul_f32_e32 v104, v93, v169
	v_and_b32_e32 v105, 0xffff0000, v51
	v_fmac_f32_e32 v103, v104, v105
	v_mul_f32_e32 v104, v92, v170
	v_lshlrev_b32_e32 v105, 16, v44
	v_fmac_f32_e32 v96, v104, v105
	v_mul_f32_e32 v104, v92, v171
	v_and_b32_e32 v105, 0xffff0000, v44
	v_fmac_f32_e32 v97, v104, v105
	v_mul_f32_e32 v104, v92, v172
	v_lshlrev_b32_e32 v105, 16, v45
	v_fmac_f32_e32 v98, v104, v105
	v_mul_f32_e32 v104, v92, v173
	v_and_b32_e32 v105, 0xffff0000, v45
	v_fmac_f32_e32 v99, v104, v105
	v_mul_f32_e32 v104, v92, v174
	v_lshlrev_b32_e32 v105, 16, v46
	v_fmac_f32_e32 v100, v104, v105
	v_mul_f32_e32 v104, v92, v175
	v_and_b32_e32 v105, 0xffff0000, v46
	v_fmac_f32_e32 v101, v104, v105
	v_mul_f32_e32 v104, v92, v176
	v_lshlrev_b32_e32 v105, 16, v47
	v_fmac_f32_e32 v102, v104, v105
	v_mul_f32_e32 v104, v92, v177
	v_and_b32_e32 v105, 0xffff0000, v47
	v_fmac_f32_e32 v103, v104, v105
	v_mul_f32_e32 v184, 0xbfb8aa3b, v96
	v_mul_f32_e32 v185, 0xbfb8aa3b, v97
	v_mul_f32_e32 v186, 0xbfb8aa3b, v98
	v_mul_f32_e32 v187, 0xbfb8aa3b, v99
	v_mul_f32_e32 v188, 0xbfb8aa3b, v100
	v_mul_f32_e32 v189, 0xbfb8aa3b, v101
	v_mul_f32_e32 v190, 0xbfb8aa3b, v102
	v_mul_f32_e32 v191, 0xbfb8aa3b, v103
	v_exp_f32_e32 v184, v184
	v_exp_f32_e32 v185, v185
	v_exp_f32_e32 v186, v186
	v_exp_f32_e32 v187, v187
	v_exp_f32_e32 v188, v188
	v_exp_f32_e32 v189, v189
	v_exp_f32_e32 v190, v190
	v_exp_f32_e32 v191, v191
	v_add_f32_e32 v184, 1.0, v184
	v_add_f32_e32 v185, 1.0, v185
	v_add_f32_e32 v186, 1.0, v186
	v_add_f32_e32 v187, 1.0, v187
	v_add_f32_e32 v188, 1.0, v188
	v_add_f32_e32 v189, 1.0, v189
	v_add_f32_e32 v190, 1.0, v190
	v_add_f32_e32 v191, 1.0, v191
	v_rcp_f32_e32 v184, v184
	v_rcp_f32_e32 v185, v185
	v_rcp_f32_e32 v186, v186
	v_rcp_f32_e32 v187, v187
	v_rcp_f32_e32 v188, v188
	v_rcp_f32_e32 v189, v189
	v_rcp_f32_e32 v190, v190
	v_rcp_f32_e32 v191, v191
	s_nop 0
	v_mul_f32_e32 v96, v96, v184
	v_mul_f32_e32 v97, v97, v185
	v_mul_f32_e32 v98, v98, v186
	v_mul_f32_e32 v99, v99, v187
	v_mul_f32_e32 v100, v100, v188
	v_mul_f32_e32 v101, v101, v189
	v_mul_f32_e32 v102, v102, v190
	v_mul_f32_e32 v103, v103, v191
	v_mul_f32_e32 v96, 0x3db504f3, v96
	v_mul_f32_e32 v97, 0x3db504f3, v97
	v_mul_f32_e32 v98, 0x3db504f3, v98
	v_mul_f32_e32 v99, 0x3db504f3, v99
	v_mul_f32_e32 v100, 0x3db504f3, v100
	v_mul_f32_e32 v101, 0x3db504f3, v101
	v_mul_f32_e32 v102, 0x3db504f3, v102
	v_mul_f32_e32 v103, 0x3db504f3, v103
	v_cvt_pk_bf16_f32 v184, v96, v96
	v_cvt_pk_bf16_f32 v185, v97, v97
	v_cvt_pk_bf16_f32 v186, v98, v98
	v_cvt_pk_bf16_f32 v187, v99, v99
	v_cvt_pk_bf16_f32 v188, v100, v100
	v_cvt_pk_bf16_f32 v189, v101, v101
	v_cvt_pk_bf16_f32 v190, v102, v102
	v_cvt_pk_bf16_f32 v191, v103, v103
	ds_write_b16 v106, v184 offset:8704
	ds_write_b16 v106, v185 offset:8976
	ds_write_b16 v106, v186 offset:9248
	ds_write_b16 v106, v187 offset:9520
	ds_write_b16 v106, v188 offset:9792
	ds_write_b16 v106, v189 offset:10064
	ds_write_b16 v106, v190 offset:10336
	ds_write_b16 v106, v191 offset:10608
	v_lshlrev_b32_e32 v105, 16, v40
	v_mul_f32_e32 v104, v80, v105
	v_mul_f32_e32 v112, v81, v105
	v_cvt_pk_bf16_f32 v104, v104, v104
	v_cvt_pk_bf16_f32 v112, v112, v112
	ds_write_b16 v106, v104 offset:43520
	ds_write_b16 v107, v112 offset:8704
	v_and_b32_e32 v105, 0xffff0000, v40
	v_mul_f32_e32 v104, v80, v105
	v_mul_f32_e32 v112, v81, v105
	v_cvt_pk_bf16_f32 v104, v104, v104
	v_cvt_pk_bf16_f32 v112, v112, v112
; __device__ __forceinline__ bf16_t f2bf(float f) { return (bf16_t)(pack2(f, 0.f) & 0xffffu); }
; __device__ void ml_local_tile(unsigned char* lds, const Params& p, int l, int b, int h, int n) {
;     ...
;     for (int i = 0; i < 4; ++i) {
;       const int ec = ec0 + 4 * i;
;       float k8[8];
;       ml_conv8_comp(ku[i], wc, 512 + h * 128 + ec * 8, L, p0 + s, k8);
;       float v8[8];
;       unpack8(vu[i], v8);
; #pragma unroll
;       for (int e = 0; e < 8; ++e) {
;         KT[(ec * 8 + e) * 136 + s] = f2bf(k8[e] * 0.08838834764831845f);
;         VF[(ec * 8 + e) * 136 + s] = f2bf(v8[e] * wf);
;         VB[(ec * 8 + e) * 136 + s] = f2bf(v8[e] * wb);
;       }
;     }
	ds_write_b16 v106, v104 offset:43792
	ds_write_b16 v107, v112 offset:8976
	v_lshlrev_b32_e32 v105, 16, v41
	v_mul_f32_e32 v104, v80, v105
	v_mul_f32_e32 v112, v81, v105
	v_cvt_pk_bf16_f32 v104, v104, v104
	v_cvt_pk_bf16_f32 v112, v112, v112
	ds_write_b16 v106, v104 offset:44064
	ds_write_b16 v107, v112 offset:9248
	v_and_b32_e32 v105, 0xffff0000, v41
	v_mul_f32_e32 v104, v80, v105
	v_mul_f32_e32 v112, v81, v105
	v_cvt_pk_bf16_f32 v104, v104, v104
	v_cvt_pk_bf16_f32 v112, v112, v112
	ds_write_b16 v106, v104 offset:44336
	ds_write_b16 v107, v112 offset:9520
	v_lshlrev_b32_e32 v105, 16, v42
	v_mul_f32_e32 v104, v80, v105
	v_mul_f32_e32 v112, v81, v105
	v_cvt_pk_bf16_f32 v104, v104, v104
	v_cvt_pk_bf16_f32 v112, v112, v112
	ds_write_b16 v106, v104 offset:44608
	ds_write_b16 v107, v112 offset:9792
	v_and_b32_e32 v105, 0xffff0000, v42
	v_mul_f32_e32 v104, v80, v105
	v_mul_f32_e32 v112, v81, v105
	v_cvt_pk_bf16_f32 v104, v104, v104
	v_cvt_pk_bf16_f32 v112, v112, v112
	ds_write_b16 v106, v104 offset:44880
	ds_write_b16 v107, v112 offset:10064
	v_lshlrev_b32_e32 v105, 16, v43
	v_mul_f32_e32 v104, v80, v105
	v_mul_f32_e32 v112, v81, v105
	v_cvt_pk_bf16_f32 v104, v104, v104
	v_cvt_pk_bf16_f32 v112, v112, v112
	ds_write_b16 v106, v104 offset:45152
	ds_write_b16 v107, v112 offset:10336
	v_and_b32_e32 v105, 0xffff0000, v43
	v_mul_f32_e32 v104, v80, v105
	v_mul_f32_e32 v112, v81, v105
	v_cvt_pk_bf16_f32 v104, v104, v104
	v_cvt_pk_bf16_f32 v112, v112, v112
	ds_write_b16 v106, v104 offset:45424
	ds_write_b16 v107, v112 offset:10608
	global_load_dwordx4 v[146:149], v[84:85], off offset:2432
	global_load_dwordx4 v[150:153], v[84:85], off offset:2448
	global_load_dwordx4 v[154:157], v[178:179], off offset:2432
	global_load_dwordx4 v[158:161], v[178:179], off offset:2448
	global_load_dwordx4 v[162:165], v[180:181], off offset:2432
	global_load_dwordx4 v[166:169], v[180:181], off offset:2448
	global_load_dwordx4 v[170:173], v[182:183], off offset:2432
	global_load_dwordx4 v[174:177], v[182:183], off offset:2448
	s_waitcnt vmcnt(8)
	v_mul_f32_e32 v104, v95, v114
	v_lshlrev_b32_e32 v105, 16, v36
	v_fma_f32 v96, v104, v105, 0
	v_mul_f32_e32 v104, v95, v115
	v_and_b32_e32 v105, 0xffff0000, v36
	v_fma_f32 v97, v104, v105, 0
	v_mul_f32_e32 v104, v95, v116
	v_lshlrev_b32_e32 v105, 16, v37
	v_fma_f32 v98, v104, v105, 0
	v_mul_f32_e32 v104, v95, v117
	v_and_b32_e32 v105, 0xffff0000, v37
	v_fma_f32 v99, v104, v105, 0
	v_mul_f32_e32 v104, v95, v118
	v_lshlrev_b32_e32 v105, 16, v38
	v_fma_f32 v100, v104, v105, 0
	v_mul_f32_e32 v104, v95, v119
	v_and_b32_e32 v105, 0xffff0000, v38
	v_fma_f32 v101, v104, v105, 0
	v_mul_f32_e32 v104, v95, v120
	v_lshlrev_b32_e32 v105, 16, v39
	v_fma_f32 v102, v104, v105, 0
	v_mul_f32_e32 v104, v95, v121
	v_and_b32_e32 v105, 0xffff0000, v39
	v_fma_f32 v103, v104, v105, 0
	v_mul_f32_e32 v104, v94, v122
	v_lshlrev_b32_e32 v105, 16, v32
	v_fmac_f32_e32 v96, v104, v105
	v_mul_f32_e32 v104, v94, v123
	v_and_b32_e32 v105, 0xffff0000, v32
	v_fmac_f32_e32 v97, v104, v105
	v_mul_f32_e32 v104, v94, v124
	v_lshlrev_b32_e32 v105, 16, v33
	v_fmac_f32_e32 v98, v104, v105
	v_mul_f32_e32 v104, v94, v125
	v_and_b32_e32 v105, 0xffff0000, v33
	v_fmac_f32_e32 v99, v104, v105
	v_mul_f32_e32 v104, v94, v126
	v_lshlrev_b32_e32 v105, 16, v34
	v_fmac_f32_e32 v100, v104, v105
	v_mul_f32_e32 v104, v94, v127
	v_and_b32_e32 v105, 0xffff0000, v34
	v_fmac_f32_e32 v101, v104, v105
	v_mul_f32_e32 v104, v94, v128
	v_lshlrev_b32_e32 v105, 16, v35
	v_fmac_f32_e32 v102, v104, v105
	v_mul_f32_e32 v104, v94, v129
	v_and_b32_e32 v105, 0xffff0000, v35
	v_fmac_f32_e32 v103, v104, v105
	v_mul_f32_e32 v104, v93, v130
	v_lshlrev_b32_e32 v105, 16, v28
	v_fmac_f32_e32 v96, v104, v105
	v_mul_f32_e32 v104, v93, v131
	v_and_b32_e32 v105, 0xffff0000, v28
	v_fmac_f32_e32 v97, v104, v105
	v_mul_f32_e32 v104, v93, v132
	v_lshlrev_b32_e32 v105, 16, v29
	v_fmac_f32_e32 v98, v104, v105
	v_mul_f32_e32 v104, v93, v133
	v_and_b32_e32 v105, 0xffff0000, v29
	v_fmac_f32_e32 v99, v104, v105
	v_mul_f32_e32 v104, v93, v134
	v_lshlrev_b32_e32 v105, 16, v30
	v_fmac_f32_e32 v100, v104, v105
	v_mul_f32_e32 v104, v93, v135
	v_and_b32_e32 v105, 0xffff0000, v30
	v_fmac_f32_e32 v101, v104, v105
	v_mul_f32_e32 v104, v93, v136
	v_lshlrev_b32_e32 v105, 16, v31
	v_fmac_f32_e32 v102, v104, v105
	v_mul_f32_e32 v104, v93, v137
	v_and_b32_e32 v105, 0xffff0000, v31
	v_fmac_f32_e32 v103, v104, v105
	v_mul_f32_e32 v104, v92, v138
	v_lshlrev_b32_e32 v105, 16, v24
	v_fmac_f32_e32 v96, v104, v105
	v_mul_f32_e32 v104, v92, v139
	v_and_b32_e32 v105, 0xffff0000, v24
	v_fmac_f32_e32 v97, v104, v105
	v_mul_f32_e32 v104, v92, v140
	v_lshlrev_b32_e32 v105, 16, v25
	v_fmac_f32_e32 v98, v104, v105
	v_mul_f32_e32 v104, v92, v141
	v_and_b32_e32 v105, 0xffff0000, v25
	v_fmac_f32_e32 v99, v104, v105
	v_mul_f32_e32 v104, v92, v142
	v_lshlrev_b32_e32 v105, 16, v26
	v_fmac_f32_e32 v100, v104, v105
	v_mul_f32_e32 v104, v92, v143
	v_and_b32_e32 v105, 0xffff0000, v26
	v_fmac_f32_e32 v101, v104, v105
	v_mul_f32_e32 v104, v92, v144
	v_lshlrev_b32_e32 v105, 16, v27
	v_fmac_f32_e32 v102, v104, v105
	v_mul_f32_e32 v104, v92, v145
	v_and_b32_e32 v105, 0xffff0000, v27
	v_fmac_f32_e32 v103, v104, v105
	v_mul_f32_e32 v184, 0xbfb8aa3b, v96
	v_mul_f32_e32 v185, 0xbfb8aa3b, v97
	v_mul_f32_e32 v186, 0xbfb8aa3b, v98
	v_mul_f32_e32 v187, 0xbfb8aa3b, v99
	v_mul_f32_e32 v188, 0xbfb8aa3b, v100
	v_mul_f32_e32 v189, 0xbfb8aa3b, v101
	v_mul_f32_e32 v190, 0xbfb8aa3b, v102
	v_mul_f32_e32 v191, 0xbfb8aa3b, v103
	v_exp_f32_e32 v184, v184
	v_exp_f32_e32 v185, v185
	v_exp_f32_e32 v186, v186
	v_exp_f32_e32 v187, v187
	v_exp_f32_e32 v188, v188
	v_exp_f32_e32 v189, v189
; __device__ __forceinline__ bf16_t f2bf(float f) { return (bf16_t)(pack2(f, 0.f) & 0xffffu); }
; __device__ void ml_local_tile(unsigned char* lds, const Params& p, int l, int b, int h, int n) {
;     ...
;     for (int i = 0; i < 4; ++i) {
;       const int ec = ec0 + 4 * i;
;       float k8[8];
;       ml_conv8_comp(ku[i], wc, 512 + h * 128 + ec * 8, L, p0 + s, k8);
;       float v8[8];
;       unpack8(vu[i], v8);
; #pragma unroll
;       for (int e = 0; e < 8; ++e) {
;         KT[(ec * 8 + e) * 136 + s] = f2bf(k8[e] * 0.08838834764831845f);
;         VF[(ec * 8 + e) * 136 + s] = f2bf(v8[e] * wf);
;         VB[(ec * 8 + e) * 136 + s] = f2bf(v8[e] * wb);
;       }
;     }
	v_exp_f32_e32 v190, v190
	v_exp_f32_e32 v191, v191
	v_add_f32_e32 v184, 1.0, v184
	v_add_f32_e32 v185, 1.0, v185
	v_add_f32_e32 v186, 1.0, v186
	v_add_f32_e32 v187, 1.0, v187
	v_add_f32_e32 v188, 1.0, v188
	v_add_f32_e32 v189, 1.0, v189
	v_add_f32_e32 v190, 1.0, v190
	v_add_f32_e32 v191, 1.0, v191
	v_rcp_f32_e32 v184, v184
	v_rcp_f32_e32 v185, v185
	v_rcp_f32_e32 v186, v186
	v_rcp_f32_e32 v187, v187
	v_rcp_f32_e32 v188, v188
	v_rcp_f32_e32 v189, v189
	v_rcp_f32_e32 v190, v190
	v_rcp_f32_e32 v191, v191
	s_nop 0
	v_mul_f32_e32 v96, v96, v184
	v_mul_f32_e32 v97, v97, v185
	v_mul_f32_e32 v98, v98, v186
	v_mul_f32_e32 v99, v99, v187
	v_mul_f32_e32 v100, v100, v188
	v_mul_f32_e32 v101, v101, v189
	v_mul_f32_e32 v102, v102, v190
	v_mul_f32_e32 v103, v103, v191
	v_mul_f32_e32 v96, 0x3db504f3, v96
	v_mul_f32_e32 v97, 0x3db504f3, v97
	v_mul_f32_e32 v98, 0x3db504f3, v98
	v_mul_f32_e32 v99, 0x3db504f3, v99
	v_mul_f32_e32 v100, 0x3db504f3, v100
	v_mul_f32_e32 v101, 0x3db504f3, v101
	v_mul_f32_e32 v102, 0x3db504f3, v102
	v_mul_f32_e32 v103, 0x3db504f3, v103
	v_cvt_pk_bf16_f32 v184, v96, v96
	v_cvt_pk_bf16_f32 v185, v97, v97
	v_cvt_pk_bf16_f32 v186, v98, v98
	v_cvt_pk_bf16_f32 v187, v99, v99
	v_cvt_pk_bf16_f32 v188, v100, v100
	v_cvt_pk_bf16_f32 v189, v101, v101
	v_cvt_pk_bf16_f32 v190, v102, v102
	v_cvt_pk_bf16_f32 v191, v103, v103
	ds_write_b16 v106, v184 offset:17408
	ds_write_b16 v106, v185 offset:17680
	ds_write_b16 v106, v186 offset:17952
	ds_write_b16 v106, v187 offset:18224
	ds_write_b16 v106, v188 offset:18496
	ds_write_b16 v106, v189 offset:18768
	ds_write_b16 v106, v190 offset:19040
	ds_write_b16 v106, v191 offset:19312
	v_lshlrev_b32_e32 v105, 16, v20
	v_mul_f32_e32 v104, v80, v105
	v_mul_f32_e32 v112, v81, v105
	v_cvt_pk_bf16_f32 v104, v104, v104
	v_cvt_pk_bf16_f32 v112, v112, v112
	ds_write_b16 v106, v104 offset:52224
	ds_write_b16 v107, v112 offset:17408
	v_and_b32_e32 v105, 0xffff0000, v20
	v_mul_f32_e32 v104, v80, v105
	v_mul_f32_e32 v112, v81, v105
	v_cvt_pk_bf16_f32 v104, v104, v104
	v_cvt_pk_bf16_f32 v112, v112, v112
	ds_write_b16 v106, v104 offset:52496
	ds_write_b16 v107, v112 offset:17680
	v_lshlrev_b32_e32 v105, 16, v21
	v_mul_f32_e32 v104, v80, v105
	v_mul_f32_e32 v112, v81, v105
	v_cvt_pk_bf16_f32 v104, v104, v104
	v_cvt_pk_bf16_f32 v112, v112, v112
	ds_write_b16 v106, v104 offset:52768
	ds_write_b16 v107, v112 offset:17952
	v_and_b32_e32 v105, 0xffff0000, v21
	v_mul_f32_e32 v104, v80, v105
	v_mul_f32_e32 v112, v81, v105
	v_cvt_pk_bf16_f32 v104, v104, v104
	v_cvt_pk_bf16_f32 v112, v112, v112
	ds_write_b16 v106, v104 offset:53040
	ds_write_b16 v107, v112 offset:18224
	v_lshlrev_b32_e32 v105, 16, v22
	v_mul_f32_e32 v104, v80, v105
	v_mul_f32_e32 v112, v81, v105
	v_cvt_pk_bf16_f32 v104, v104, v104
	v_cvt_pk_bf16_f32 v112, v112, v112
	ds_write_b16 v106, v104 offset:53312
	ds_write_b16 v107, v112 offset:18496
	v_and_b32_e32 v105, 0xffff0000, v22
	v_mul_f32_e32 v104, v80, v105
	v_mul_f32_e32 v112, v81, v105
	v_cvt_pk_bf16_f32 v104, v104, v104
	v_cvt_pk_bf16_f32 v112, v112, v112
	ds_write_b16 v106, v104 offset:53584
	ds_write_b16 v107, v112 offset:18768
	v_lshlrev_b32_e32 v105, 16, v23
	v_mul_f32_e32 v104, v80, v105
	v_mul_f32_e32 v112, v81, v105
	v_cvt_pk_bf16_f32 v104, v104, v104
	v_cvt_pk_bf16_f32 v112, v112, v112
	ds_write_b16 v106, v104 offset:53856
	ds_write_b16 v107, v112 offset:19040
	v_and_b32_e32 v105, 0xffff0000, v23
	v_mul_f32_e32 v104, v80, v105
	v_mul_f32_e32 v112, v81, v105
	v_cvt_pk_bf16_f32 v104, v104, v104
	v_cvt_pk_bf16_f32 v112, v112, v112
	ds_write_b16 v106, v104 offset:54128
	ds_write_b16 v107, v112 offset:19312
	s_waitcnt vmcnt(0)
	v_mul_f32_e32 v104, v95, v146
	v_lshlrev_b32_e32 v105, 16, v16
	v_fma_f32 v96, v104, v105, 0
	v_mul_f32_e32 v104, v95, v147
	v_and_b32_e32 v105, 0xffff0000, v16
	v_fma_f32 v97, v104, v105, 0
	v_mul_f32_e32 v104, v95, v148
	v_lshlrev_b32_e32 v105, 16, v17
	v_fma_f32 v98, v104, v105, 0
	v_mul_f32_e32 v104, v95, v149
	v_and_b32_e32 v105, 0xffff0000, v17
	v_fma_f32 v99, v104, v105, 0
	v_mul_f32_e32 v104, v95, v150
	v_lshlrev_b32_e32 v105, 16, v18
	v_fma_f32 v100, v104, v105, 0
	v_mul_f32_e32 v104, v95, v151
	v_and_b32_e32 v105, 0xffff0000, v18
	v_fma_f32 v101, v104, v105, 0
	v_mul_f32_e32 v104, v95, v152
	v_lshlrev_b32_e32 v105, 16, v19
	v_fma_f32 v102, v104, v105, 0
	v_mul_f32_e32 v104, v95, v153
	v_and_b32_e32 v105, 0xffff0000, v19
	v_fma_f32 v103, v104, v105, 0
	v_mul_f32_e32 v104, v94, v154
	v_lshlrev_b32_e32 v105, 16, v12
	v_fmac_f32_e32 v96, v104, v105
	v_mul_f32_e32 v104, v94, v155
	v_and_b32_e32 v105, 0xffff0000, v12
	v_fmac_f32_e32 v97, v104, v105
	v_mul_f32_e32 v104, v94, v156
	v_lshlrev_b32_e32 v105, 16, v13
	v_fmac_f32_e32 v98, v104, v105
	v_mul_f32_e32 v104, v94, v157
	v_and_b32_e32 v105, 0xffff0000, v13
	v_fmac_f32_e32 v99, v104, v105
	v_mul_f32_e32 v104, v94, v158
	v_lshlrev_b32_e32 v105, 16, v14
	v_fmac_f32_e32 v100, v104, v105
	v_mul_f32_e32 v104, v94, v159
	v_and_b32_e32 v105, 0xffff0000, v14
	v_fmac_f32_e32 v101, v104, v105
	v_mul_f32_e32 v104, v94, v160
	v_lshlrev_b32_e32 v105, 16, v15
	v_fmac_f32_e32 v102, v104, v105
	v_mul_f32_e32 v104, v94, v161
	v_and_b32_e32 v105, 0xffff0000, v15
	v_fmac_f32_e32 v103, v104, v105
	v_mul_f32_e32 v104, v93, v162
	v_lshlrev_b32_e32 v105, 16, v8
	v_fmac_f32_e32 v96, v104, v105
	v_mul_f32_e32 v104, v93, v163
	v_and_b32_e32 v105, 0xffff0000, v8
	v_fmac_f32_e32 v97, v104, v105
	v_mul_f32_e32 v104, v93, v164
	v_lshlrev_b32_e32 v105, 16, v9
	v_fmac_f32_e32 v98, v104, v105
	v_mul_f32_e32 v104, v93, v165
	v_and_b32_e32 v105, 0xffff0000, v9
	v_fmac_f32_e32 v99, v104, v105
	v_mul_f32_e32 v104, v93, v166
	v_lshlrev_b32_e32 v105, 16, v10
; __device__ __forceinline__ bf16_t f2bf(float f) { return (bf16_t)(pack2(f, 0.f) & 0xffffu); }
; __device__ void ml_local_tile(unsigned char* lds, const Params& p, int l, int b, int h, int n) {
;     ...
;       ml_conv8_comp(ku[i], wc, 512 + h * 128 + ec * 8, L, p0 + s, k8);
;       float v8[8];
;       unpack8(vu[i], v8);
; #pragma unroll
;       for (int e = 0; e < 8; ++e) {
;         KT[(ec * 8 + e) * 136 + s] = f2bf(k8[e] * 0.08838834764831845f);
;         VF[(ec * 8 + e) * 136 + s] = f2bf(v8[e] * wf);
;         VB[(ec * 8 + e) * 136 + s] = f2bf(v8[e] * wb);
;       }
;     }
;   }
;   __syncthreads();
	v_fmac_f32_e32 v100, v104, v105
	v_mul_f32_e32 v104, v93, v167
	v_and_b32_e32 v105, 0xffff0000, v10
	v_fmac_f32_e32 v101, v104, v105
	v_mul_f32_e32 v104, v93, v168
	v_lshlrev_b32_e32 v105, 16, v11
	v_fmac_f32_e32 v102, v104, v105
	v_mul_f32_e32 v104, v93, v169
	v_and_b32_e32 v105, 0xffff0000, v11
	v_fmac_f32_e32 v103, v104, v105
	v_mul_f32_e32 v104, v92, v170
	v_lshlrev_b32_e32 v105, 16, v4
	v_fmac_f32_e32 v96, v104, v105
	v_mul_f32_e32 v104, v92, v171
	v_and_b32_e32 v105, 0xffff0000, v4
	v_fmac_f32_e32 v97, v104, v105
	v_mul_f32_e32 v104, v92, v172
	v_lshlrev_b32_e32 v105, 16, v5
	v_fmac_f32_e32 v98, v104, v105
	v_mul_f32_e32 v104, v92, v173
	v_and_b32_e32 v105, 0xffff0000, v5
	v_fmac_f32_e32 v99, v104, v105
	v_mul_f32_e32 v104, v92, v174
	v_lshlrev_b32_e32 v105, 16, v6
	v_fmac_f32_e32 v100, v104, v105
	v_mul_f32_e32 v104, v92, v175
	v_and_b32_e32 v105, 0xffff0000, v6
	v_fmac_f32_e32 v101, v104, v105
	v_mul_f32_e32 v104, v92, v176
	v_lshlrev_b32_e32 v105, 16, v7
	v_fmac_f32_e32 v102, v104, v105
	v_mul_f32_e32 v104, v92, v177
	v_and_b32_e32 v105, 0xffff0000, v7
	v_fmac_f32_e32 v103, v104, v105
	v_mul_f32_e32 v184, 0xbfb8aa3b, v96
	v_mul_f32_e32 v185, 0xbfb8aa3b, v97
	v_mul_f32_e32 v186, 0xbfb8aa3b, v98
	v_mul_f32_e32 v187, 0xbfb8aa3b, v99
	v_mul_f32_e32 v188, 0xbfb8aa3b, v100
	v_mul_f32_e32 v189, 0xbfb8aa3b, v101
	v_mul_f32_e32 v190, 0xbfb8aa3b, v102
	v_mul_f32_e32 v191, 0xbfb8aa3b, v103
	v_exp_f32_e32 v184, v184
	v_exp_f32_e32 v185, v185
	v_exp_f32_e32 v186, v186
	v_exp_f32_e32 v187, v187
	v_exp_f32_e32 v188, v188
	v_exp_f32_e32 v189, v189
	v_exp_f32_e32 v190, v190
	v_exp_f32_e32 v191, v191
	v_add_f32_e32 v184, 1.0, v184
	v_add_f32_e32 v185, 1.0, v185
	v_add_f32_e32 v186, 1.0, v186
	v_add_f32_e32 v187, 1.0, v187
	v_add_f32_e32 v188, 1.0, v188
	v_add_f32_e32 v189, 1.0, v189
	v_add_f32_e32 v190, 1.0, v190
	v_add_f32_e32 v191, 1.0, v191
	v_rcp_f32_e32 v184, v184
	v_rcp_f32_e32 v185, v185
	v_rcp_f32_e32 v186, v186
	v_rcp_f32_e32 v187, v187
	v_rcp_f32_e32 v188, v188
	v_rcp_f32_e32 v189, v189
	v_rcp_f32_e32 v190, v190
	v_rcp_f32_e32 v191, v191
	s_nop 0
	v_mul_f32_e32 v96, v96, v184
	v_mul_f32_e32 v97, v97, v185
	v_mul_f32_e32 v98, v98, v186
	v_mul_f32_e32 v99, v99, v187
	v_mul_f32_e32 v100, v100, v188
	v_mul_f32_e32 v101, v101, v189
	v_mul_f32_e32 v102, v102, v190
	v_mul_f32_e32 v103, v103, v191
	v_mul_f32_e32 v96, 0x3db504f3, v96
	v_mul_f32_e32 v97, 0x3db504f3, v97
	v_mul_f32_e32 v98, 0x3db504f3, v98
	v_mul_f32_e32 v99, 0x3db504f3, v99
	v_mul_f32_e32 v100, 0x3db504f3, v100
	v_mul_f32_e32 v101, 0x3db504f3, v101
	v_mul_f32_e32 v102, 0x3db504f3, v102
	v_mul_f32_e32 v103, 0x3db504f3, v103
	v_cvt_pk_bf16_f32 v184, v96, v96
	v_cvt_pk_bf16_f32 v185, v97, v97
	v_cvt_pk_bf16_f32 v186, v98, v98
	v_cvt_pk_bf16_f32 v187, v99, v99
	v_cvt_pk_bf16_f32 v188, v100, v100
	v_cvt_pk_bf16_f32 v189, v101, v101
	v_cvt_pk_bf16_f32 v190, v102, v102
	v_cvt_pk_bf16_f32 v191, v103, v103
	ds_write_b16 v106, v184 offset:26112
	ds_write_b16 v106, v185 offset:26384
	ds_write_b16 v106, v186 offset:26656
	ds_write_b16 v106, v187 offset:26928
	ds_write_b16 v106, v188 offset:27200
	ds_write_b16 v106, v189 offset:27472
	ds_write_b16 v106, v190 offset:27744
	ds_write_b16 v106, v191 offset:28016
	v_lshlrev_b32_e32 v105, 16, v0
	v_mul_f32_e32 v104, v80, v105
	v_mul_f32_e32 v112, v81, v105
	v_cvt_pk_bf16_f32 v104, v104, v104
	v_cvt_pk_bf16_f32 v112, v112, v112
	ds_write_b16 v106, v104 offset:60928
	ds_write_b16 v107, v112 offset:26112
	v_and_b32_e32 v105, 0xffff0000, v0
	v_mul_f32_e32 v104, v80, v105
	v_mul_f32_e32 v112, v81, v105
	v_cvt_pk_bf16_f32 v104, v104, v104
	v_cvt_pk_bf16_f32 v112, v112, v112
	ds_write_b16 v106, v104 offset:61200
	ds_write_b16 v107, v112 offset:26384
	v_lshlrev_b32_e32 v105, 16, v1
	v_mul_f32_e32 v104, v80, v105
	v_mul_f32_e32 v112, v81, v105
	v_cvt_pk_bf16_f32 v104, v104, v104
	v_cvt_pk_bf16_f32 v112, v112, v112
	ds_write_b16 v106, v104 offset:61472
	ds_write_b16 v107, v112 offset:26656
	v_and_b32_e32 v105, 0xffff0000, v1
	v_mul_f32_e32 v104, v80, v105
	v_mul_f32_e32 v112, v81, v105
	v_cvt_pk_bf16_f32 v104, v104, v104
	v_cvt_pk_bf16_f32 v112, v112, v112
	ds_write_b16 v106, v104 offset:61744
	ds_write_b16 v107, v112 offset:26928
	v_lshlrev_b32_e32 v105, 16, v2
	v_mul_f32_e32 v104, v80, v105
	v_mul_f32_e32 v112, v81, v105
	v_cvt_pk_bf16_f32 v104, v104, v104
	v_cvt_pk_bf16_f32 v112, v112, v112
	ds_write_b16 v106, v104 offset:62016
	ds_write_b16 v107, v112 offset:27200
	v_and_b32_e32 v105, 0xffff0000, v2
	v_mul_f32_e32 v104, v80, v105
	v_mul_f32_e32 v112, v81, v105
	v_cvt_pk_bf16_f32 v104, v104, v104
	v_cvt_pk_bf16_f32 v112, v112, v112
	ds_write_b16 v106, v104 offset:62288
	ds_write_b16 v107, v112 offset:27472
	v_lshlrev_b32_e32 v105, 16, v3
	v_mul_f32_e32 v104, v80, v105
	v_mul_f32_e32 v112, v81, v105
	v_cvt_pk_bf16_f32 v104, v104, v104
	v_cvt_pk_bf16_f32 v112, v112, v112
	ds_write_b16 v106, v104 offset:62560
	ds_write_b16 v107, v112 offset:27744
	v_and_b32_e32 v105, 0xffff0000, v3
	v_mul_f32_e32 v104, v80, v105
	v_mul_f32_e32 v112, v81, v105
	v_cvt_pk_bf16_f32 v104, v104, v104
	v_cvt_pk_bf16_f32 v112, v112, v112
	ds_write_b16 v106, v104 offset:62832
	ds_write_b16 v107, v112 offset:28016
	v_lshl_or_b32 v0, v89, 4, v90
	v_lshlrev_b32_e32 v1, 4, v91
	v_mul_lo_u32 v0, v0, s93
	v_add_u32_e32 v8, 0, v1
	v_add_u32_e32 v9, v8, v0
	v_mad_u32_u24 v8, v90, s93, v8
	s_and_b32 s2, s21, -4
	s_ashr_i32 s21, s20, 31
	s_waitcnt lgkmcnt(0)
	s_barrier
; __device__ void ml_local_tile(unsigned char* lds, const Params& p, int l, int b, int h, int n) {
;     ...
;   {
;     f32x4 accf[8], accb[8];
; #pragma unroll
;     for (int i = 0; i < 8; ++i) { accf[i] = (f32x4){0.f, 0.f, 0.f, 0.f}; accb[i] = (f32x4){0.f, 0.f, 0.f, 0.f}; }
; #pragma unroll
;     for (int ks = 0; ks < 4; ++ks) {
;       const bf16x8 bfv = ldfrag(VF + (16 * w + lr) * 136 + ks * 32 + lg * 8);
;       const bf16x8 bbv = ldfrag(VB + (16 * w + lr) * 136 + ks * 32 + lg * 8);
; #pragma unroll
;       for (int ef = 0; ef < 8; ++ef) {
;         const bf16x8 a = ldfrag(KT + (ef * 16 + lr) * 136 + ks * 32 + lg * 8);
;         accf[ef] = mfma16(a, bfv, accf[ef]);
;         accb[ef] = mfma16(a, bbv, accb[ef]);
;       }
;     }
	v_add3_u32 v78, s0, v0, v1
	ds_read_b128 v[0:3], v9 offset:34816
	ds_read_b128 v[4:7], v78
	ds_read_b128 v[10:13], v8
	ds_read_b128 v[18:21], v8 offset:4352
	ds_read_b128 v[26:29], v8 offset:8704
	ds_read_b128 v[34:37], v8 offset:13056
	ds_read_b128 v[42:45], v8 offset:17408
	ds_read_b128 v[50:53], v8 offset:21760
	ds_read_b128 v[58:61], v8 offset:26112
	ds_read_b128 v[66:69], v8 offset:30464
	s_waitcnt lgkmcnt(7)
	v_mfma_f32_16x16x32_bf16 v[14:17], v[10:13], v[0:3], 0
	s_lshl_b64 s[0:1], s[20:21], 15
	s_add_u32 s0, s82, s0
	s_addc_u32 s1, s83, s1
	v_mfma_f32_16x16x32_bf16 v[10:13], v[10:13], v[4:7], 0
	s_waitcnt lgkmcnt(6)
	v_mfma_f32_16x16x32_bf16 v[22:25], v[18:21], v[0:3], 0
	v_mfma_f32_16x16x32_bf16 v[18:21], v[18:21], v[4:7], 0
	s_waitcnt lgkmcnt(5)
	v_mfma_f32_16x16x32_bf16 v[30:33], v[26:29], v[0:3], 0
	v_mfma_f32_16x16x32_bf16 v[26:29], v[26:29], v[4:7], 0
	s_waitcnt lgkmcnt(4)
	v_mfma_f32_16x16x32_bf16 v[38:41], v[34:37], v[0:3], 0
	v_mfma_f32_16x16x32_bf16 v[34:37], v[34:37], v[4:7], 0
	s_waitcnt lgkmcnt(3)
	v_mfma_f32_16x16x32_bf16 v[46:49], v[42:45], v[0:3], 0
	v_mfma_f32_16x16x32_bf16 v[42:45], v[42:45], v[4:7], 0
	s_waitcnt lgkmcnt(2)
	v_mfma_f32_16x16x32_bf16 v[54:57], v[50:53], v[0:3], 0
	v_mfma_f32_16x16x32_bf16 v[50:53], v[50:53], v[4:7], 0
	s_waitcnt lgkmcnt(1)
	v_mfma_f32_16x16x32_bf16 v[62:65], v[58:61], v[0:3], 0
	v_mfma_f32_16x16x32_bf16 v[58:61], v[58:61], v[4:7], 0
	s_waitcnt lgkmcnt(0)
	v_mfma_f32_16x16x32_bf16 v[0:3], v[66:69], v[0:3], 0
	v_mfma_f32_16x16x32_bf16 v[4:7], v[66:69], v[4:7], 0
	ds_read_b128 v[66:69], v9 offset:34880
	ds_read_b128 v[70:73], v78 offset:64
	ds_read_b128 v[74:77], v8 offset:64
	s_waitcnt lgkmcnt(0)
	v_mfma_f32_16x16x32_bf16 v[14:17], v[74:77], v[66:69], v[14:17]
	v_mfma_f32_16x16x32_bf16 v[10:13], v[74:77], v[70:73], v[10:13]
	ds_read_b128 v[74:77], v8 offset:4416
	s_waitcnt lgkmcnt(0)
	v_mfma_f32_16x16x32_bf16 v[22:25], v[74:77], v[66:69], v[22:25]
	v_mfma_f32_16x16x32_bf16 v[18:21], v[74:77], v[70:73], v[18:21]
	ds_read_b128 v[74:77], v8 offset:8768
	s_waitcnt lgkmcnt(0)
	v_mfma_f32_16x16x32_bf16 v[30:33], v[74:77], v[66:69], v[30:33]
	v_mfma_f32_16x16x32_bf16 v[26:29], v[74:77], v[70:73], v[26:29]
	ds_read_b128 v[74:77], v8 offset:13120
	s_waitcnt lgkmcnt(0)
	v_mfma_f32_16x16x32_bf16 v[38:41], v[74:77], v[66:69], v[38:41]
	v_mfma_f32_16x16x32_bf16 v[34:37], v[74:77], v[70:73], v[34:37]
	ds_read_b128 v[74:77], v8 offset:17472
	s_waitcnt lgkmcnt(0)
	v_mfma_f32_16x16x32_bf16 v[46:49], v[74:77], v[66:69], v[46:49]
	v_mfma_f32_16x16x32_bf16 v[42:45], v[74:77], v[70:73], v[42:45]
	ds_read_b128 v[74:77], v8 offset:21824
	s_waitcnt lgkmcnt(0)
	v_mfma_f32_16x16x32_bf16 v[54:57], v[74:77], v[66:69], v[54:57]
	v_mfma_f32_16x16x32_bf16 v[50:53], v[74:77], v[70:73], v[50:53]
	ds_read_b128 v[74:77], v8 offset:26176
	s_waitcnt lgkmcnt(0)
	v_mfma_f32_16x16x32_bf16 v[62:65], v[74:77], v[66:69], v[62:65]
	v_mfma_f32_16x16x32_bf16 v[58:61], v[74:77], v[70:73], v[58:61]
	ds_read_b128 v[74:77], v8 offset:30528
	s_waitcnt lgkmcnt(0)
	v_mfma_f32_16x16x32_bf16 v[0:3], v[74:77], v[66:69], v[0:3]
	v_mfma_f32_16x16x32_bf16 v[66:69], v[74:77], v[70:73], v[4:7]
	s_nop 2
	ds_read_b128 v[4:7], v9 offset:34944
	ds_read_b128 v[70:73], v78 offset:128
	ds_read_b128 v[74:77], v8 offset:128
	s_waitcnt lgkmcnt(0)
	v_mfma_f32_16x16x32_bf16 v[14:17], v[74:77], v[4:7], v[14:17]
	v_mfma_f32_16x16x32_bf16 v[10:13], v[74:77], v[70:73], v[10:13]
	ds_read_b128 v[74:77], v8 offset:4480
	s_waitcnt lgkmcnt(0)
	v_mfma_f32_16x16x32_bf16 v[22:25], v[74:77], v[4:7], v[22:25]
	v_mfma_f32_16x16x32_bf16 v[18:21], v[74:77], v[70:73], v[18:21]
	ds_read_b128 v[74:77], v8 offset:8832
	s_waitcnt lgkmcnt(0)
	v_mfma_f32_16x16x32_bf16 v[30:33], v[74:77], v[4:7], v[30:33]
	v_mfma_f32_16x16x32_bf16 v[26:29], v[74:77], v[70:73], v[26:29]
	ds_read_b128 v[74:77], v8 offset:13184
	s_waitcnt lgkmcnt(0)
	v_mfma_f32_16x16x32_bf16 v[38:41], v[74:77], v[4:7], v[38:41]
	v_mfma_f32_16x16x32_bf16 v[34:37], v[74:77], v[70:73], v[34:37]
	ds_read_b128 v[74:77], v8 offset:17536
	s_waitcnt lgkmcnt(0)
	v_mfma_f32_16x16x32_bf16 v[46:49], v[74:77], v[4:7], v[46:49]
	v_mfma_f32_16x16x32_bf16 v[42:45], v[74:77], v[70:73], v[42:45]
	ds_read_b128 v[74:77], v8 offset:21888
	s_waitcnt lgkmcnt(0)
	v_mfma_f32_16x16x32_bf16 v[54:57], v[74:77], v[4:7], v[54:57]
	v_mfma_f32_16x16x32_bf16 v[50:53], v[74:77], v[70:73], v[50:53]
	ds_read_b128 v[74:77], v8 offset:26240
	s_waitcnt lgkmcnt(0)
	v_mfma_f32_16x16x32_bf16 v[62:65], v[74:77], v[4:7], v[62:65]
	v_mfma_f32_16x16x32_bf16 v[58:61], v[74:77], v[70:73], v[58:61]
	ds_read_b128 v[74:77], v8 offset:30592
	s_waitcnt lgkmcnt(0)
	v_mfma_f32_16x16x32_bf16 v[4:7], v[74:77], v[4:7], v[0:3]
	v_mfma_f32_16x16x32_bf16 v[0:3], v[74:77], v[70:73], v[66:69]
	s_nop 2
	ds_read_b128 v[66:69], v9 offset:35008
	ds_read_b128 v[70:73], v78 offset:192
	ds_read_b128 v[74:77], v8 offset:192
	s_waitcnt lgkmcnt(0)
	v_mfma_f32_16x16x32_bf16 v[14:17], v[74:77], v[66:69], v[14:17]
	v_mfma_f32_16x16x32_bf16 v[10:13], v[74:77], v[70:73], v[10:13]
	ds_read_b128 v[74:77], v8 offset:4544
	s_nop 5
	v_cvt_pk_bf16_f32 v14, v14, v15
	v_cvt_pk_bf16_f32 v15, v16, v17
	s_waitcnt lgkmcnt(0)
	v_mfma_f32_16x16x32_bf16 v[22:25], v[74:77], v[66:69], v[22:25]
	v_cvt_pk_bf16_f32 v10, v10, v11
	v_cvt_pk_bf16_f32 v11, v12, v13
	v_mfma_f32_16x16x32_bf16 v[18:21], v[74:77], v[70:73], v[18:21]
	ds_read_b128 v[74:77], v8 offset:8896
	s_waitcnt lgkmcnt(0)
	v_mfma_f32_16x16x32_bf16 v[30:33], v[74:77], v[66:69], v[30:33]
	v_mfma_f32_16x16x32_bf16 v[26:29], v[74:77], v[70:73], v[26:29]
	ds_read_b128 v[74:77], v8 offset:13248
	s_waitcnt lgkmcnt(0)
; __device__ __forceinline__ float bf2f(bf16_t h) { return __uint_as_float(((unsigned)h) << 16); }
; __device__ __forceinline__ int sidx(int dir, int b, int h, int n) { return ((dir * 8 + b) * 4 + h) * 18 + n; }
; __device__ void ml_local_tile(unsigned char* lds, const Params& p, int l, int b, int h, int n) {
;     ...
;     bf16_t* cf = Cst + (size_t)sidx(0, b, h, n) * 16384 + (16 * w + lr) * 128;
;     bf16_t* cb = Cst + (size_t)sidx(1, b, h, n) * 16384 + (16 * w + lr) * 128;
; #pragma unroll
;     for (int ef = 0; ef < 8; ++ef) {
;       uint2 u; u.x = pack2(accf[ef][0], accf[ef][1]); u.y = pack2(accf[ef][2], accf[ef][3]);
;       *(uint2*)(cf + ef * 16 + lg * 4) = u;
;       uint2 u2; u2.x = pack2(accb[ef][0], accb[ef][1]); u2.y = pack2(accb[ef][2], accb[ef][3]);
;       *(uint2*)(cb + ef * 16 + lg * 4) = u2;
;     }
;   }
;   if (tid < 256) {
;     const int e = tid & 127, dir = tid >> 7;
;     const float* wv = vec + (6 + dir) * 128;
;     float s = 0.f;
;     for (int q = 0; q < 128; ++q) s += wv[q] * bf2f(KT[e * 136 + q]);
;     nst[(size_t)sidx(dir, b, h, n) * 128 + e] = s;
;   }
	v_mfma_f32_16x16x32_bf16 v[38:41], v[74:77], v[66:69], v[38:41]
	v_mfma_f32_16x16x32_bf16 v[34:37], v[74:77], v[70:73], v[34:37]
	ds_read_b128 v[74:77], v8 offset:17600
	s_waitcnt lgkmcnt(0)
	v_mfma_f32_16x16x32_bf16 v[46:49], v[74:77], v[66:69], v[46:49]
	v_mfma_f32_16x16x32_bf16 v[42:45], v[74:77], v[70:73], v[42:45]
	ds_read_b128 v[74:77], v8 offset:21952
	s_waitcnt lgkmcnt(0)
	v_mfma_f32_16x16x32_bf16 v[54:57], v[74:77], v[66:69], v[54:57]
	v_mfma_f32_16x16x32_bf16 v[50:53], v[74:77], v[70:73], v[50:53]
	ds_read_b128 v[74:77], v8 offset:26304
	s_waitcnt lgkmcnt(0)
	v_mfma_f32_16x16x32_bf16 v[62:65], v[74:77], v[66:69], v[62:65]
	v_mfma_f32_16x16x32_bf16 v[58:61], v[74:77], v[70:73], v[58:61]
	ds_read_b128 v[74:77], v8 offset:30656
	v_lshlrev_b32_e32 v8, 7, v90
	v_lshl_or_b32 v8, v89, 11, v8
	v_ashrrev_i32_e32 v9, 31, v8
	v_lshlrev_b64 v[8:9], 1, v[8:9]
	s_waitcnt lgkmcnt(0)
	v_mfma_f32_16x16x32_bf16 v[4:7], v[74:77], v[66:69], v[4:7]
	v_lshl_add_u64 v[66:67], s[0:1], 0, v[8:9]
	s_or_b32 s0, s2, s25
	s_mul_i32 s0, s0, 18
	s_add_i32 s0, s0, s24
	s_addk_i32 s0, 0x240
	s_ashr_i32 s1, s0, 31
	s_lshl_b64 s[0:1], s[0:1], 15
	s_add_u32 s0, s82, s0
	s_addc_u32 s1, s83, s1
	v_lshl_add_u64 v[8:9], s[0:1], 0, v[8:9]
	v_lshl_add_u64 v[66:67], v[66:67], 0, v[192:193]
	v_lshl_add_u64 v[8:9], v[8:9], 0, v[192:193]
	global_store_dwordx2 v[66:67], v[14:15], off
	global_store_dwordx2 v[8:9], v[10:11], off
	v_cvt_pk_bf16_f32 v10, v22, v23
	v_cvt_pk_bf16_f32 v11, v24, v25
	global_store_dwordx2 v[66:67], v[10:11], off offset:32
	v_cvt_pk_bf16_f32 v10, v18, v19
	v_cvt_pk_bf16_f32 v11, v20, v21
	global_store_dwordx2 v[8:9], v[10:11], off offset:32
	v_cvt_pk_bf16_f32 v10, v30, v31
	v_cvt_pk_bf16_f32 v11, v32, v33
	global_store_dwordx2 v[66:67], v[10:11], off offset:64
	v_cvt_pk_bf16_f32 v10, v26, v27
	v_cvt_pk_bf16_f32 v11, v28, v29
	global_store_dwordx2 v[8:9], v[10:11], off offset:64
	v_cvt_pk_bf16_f32 v10, v38, v39
	v_cvt_pk_bf16_f32 v11, v40, v41
	global_store_dwordx2 v[66:67], v[10:11], off offset:96
	v_cvt_pk_bf16_f32 v10, v34, v35
	v_cvt_pk_bf16_f32 v11, v36, v37
	global_store_dwordx2 v[8:9], v[10:11], off offset:96
	v_cvt_pk_bf16_f32 v10, v46, v47
	v_cvt_pk_bf16_f32 v11, v48, v49
	v_mfma_f32_16x16x32_bf16 v[0:3], v[74:77], v[70:73], v[0:3]
	global_store_dwordx2 v[66:67], v[10:11], off offset:128
	v_cvt_pk_bf16_f32 v10, v42, v43
	v_cvt_pk_bf16_f32 v11, v44, v45
	global_store_dwordx2 v[8:9], v[10:11], off offset:128
	v_cvt_pk_bf16_f32 v10, v54, v55
	v_cvt_pk_bf16_f32 v11, v56, v57
	global_store_dwordx2 v[66:67], v[10:11], off offset:160
	v_cvt_pk_bf16_f32 v10, v50, v51
	v_cvt_pk_bf16_f32 v11, v52, v53
	global_store_dwordx2 v[8:9], v[10:11], off offset:160
	v_cvt_pk_bf16_f32 v10, v62, v63
	v_cvt_pk_bf16_f32 v11, v64, v65
	s_movk_i32 s0, 0x100
	global_store_dwordx2 v[66:67], v[10:11], off offset:192
	v_cvt_pk_bf16_f32 v10, v58, v59
	v_cvt_pk_bf16_f32 v11, v60, v61
	v_cvt_pk_bf16_f32 v4, v4, v5
	v_cvt_pk_bf16_f32 v5, v6, v7
	v_cvt_pk_bf16_f32 v0, v0, v1
	v_cvt_pk_bf16_f32 v1, v2, v3
	v_cmp_gt_i32_e32 vcc, s0, v88
	global_store_dwordx2 v[8:9], v[10:11], off offset:192
	global_store_dwordx2 v[66:67], v[4:5], off offset:224
	global_store_dwordx2 v[8:9], v[0:1], off offset:224
	s_and_saveexec_b64 s[0:1], vcc
	s_cbranch_execz .LBB0_321
	v_lshlrev_b32_e32 v0, 2, v88
	v_and_b32_e32 v0, 0xfffffe00, v0
	v_mad_u32_u24 v1, v86, s93, 0
	s_movk_i32 s3, 0xfe00
	v_add_u32_e32 v2, 0, v0
	v_mov_b32_e32 v0, 0
	v_add_u32_e32 v3, 0x1a400, v2
	v_mov_b32_e32 v52, 0
	v_mov_b32_e32 v53, 0
	v_mov_b32_e32 v54, 0
	v_mov_b32_e32 v55, 0
	ds_read_b128 v[4:7], v1 offset:0
	ds_read_b128 v[8:11], v1 offset:16
	ds_read_b128 v[12:15], v3 offset:0
	ds_read_b128 v[16:19], v3 offset:16
	ds_read_b128 v[20:23], v3 offset:32
	ds_read_b128 v[24:27], v3 offset:48
	ds_read_b128 v[28:31], v1 offset:32
	ds_read_b128 v[32:35], v1 offset:48
	ds_read_b128 v[36:39], v3 offset:64
	ds_read_b128 v[40:43], v3 offset:80
	ds_read_b128 v[44:47], v3 offset:96
	ds_read_b128 v[48:51], v3 offset:112
	s_waitcnt lgkmcnt(6)
	v_lshlrev_b32_e32 v56, 16, v4
	v_fmac_f32_e32 v52, v12, v56
	v_and_b32_e32 v56, 0xffff0000, v4
	v_fmac_f32_e32 v53, v13, v56
	v_lshlrev_b32_e32 v56, 16, v5
	v_fmac_f32_e32 v54, v14, v56
	v_and_b32_e32 v56, 0xffff0000, v5
	v_fmac_f32_e32 v55, v15, v56
	v_lshlrev_b32_e32 v56, 16, v6
	v_fmac_f32_e32 v52, v16, v56
	v_and_b32_e32 v56, 0xffff0000, v6
	v_fmac_f32_e32 v53, v17, v56
	v_lshlrev_b32_e32 v56, 16, v7
	v_fmac_f32_e32 v54, v18, v56
	v_and_b32_e32 v56, 0xffff0000, v7
	v_fmac_f32_e32 v55, v19, v56
	v_lshlrev_b32_e32 v56, 16, v8
	v_fmac_f32_e32 v52, v20, v56
	v_and_b32_e32 v56, 0xffff0000, v8
	v_fmac_f32_e32 v53, v21, v56
	v_lshlrev_b32_e32 v56, 16, v9
	v_fmac_f32_e32 v54, v22, v56
	v_and_b32_e32 v56, 0xffff0000, v9
	v_fmac_f32_e32 v55, v23, v56
	v_lshlrev_b32_e32 v56, 16, v10
	v_fmac_f32_e32 v52, v24, v56
	v_and_b32_e32 v56, 0xffff0000, v10
	v_fmac_f32_e32 v53, v25, v56
	v_lshlrev_b32_e32 v56, 16, v11
	v_fmac_f32_e32 v54, v26, v56
	v_and_b32_e32 v56, 0xffff0000, v11
	v_fmac_f32_e32 v55, v27, v56
	ds_read_b128 v[4:7], v1 offset:64
	ds_read_b128 v[8:11], v1 offset:80
	ds_read_b128 v[12:15], v3 offset:128
	ds_read_b128 v[16:19], v3 offset:144
	ds_read_b128 v[20:23], v3 offset:160
	ds_read_b128 v[24:27], v3 offset:176
	s_waitcnt lgkmcnt(6)
; __device__ __forceinline__ float bf2f(bf16_t h) { return __uint_as_float(((unsigned)h) << 16); }
; __device__ __forceinline__ int sidx(int dir, int b, int h, int n) { return ((dir * 8 + b) * 4 + h) * 18 + n; }
; __device__ void ml_local_tile(unsigned char* lds, const Params& p, int l, int b, int h, int n) {
;     ...
;   if (tid < 256) {
;     const int e = tid & 127, dir = tid >> 7;
;     const float* wv = vec + (6 + dir) * 128;
;     float s = 0.f;
;     for (int q = 0; q < 128; ++q) s += wv[q] * bf2f(KT[e * 136 + q]);
;     nst[(size_t)sidx(dir, b, h, n) * 128 + e] = s;
	v_lshlrev_b32_e32 v56, 16, v28
	v_fmac_f32_e32 v52, v36, v56
	v_and_b32_e32 v56, 0xffff0000, v28
	v_fmac_f32_e32 v53, v37, v56
	v_lshlrev_b32_e32 v56, 16, v29
	v_fmac_f32_e32 v54, v38, v56
	v_and_b32_e32 v56, 0xffff0000, v29
	v_fmac_f32_e32 v55, v39, v56
	v_lshlrev_b32_e32 v56, 16, v30
	v_fmac_f32_e32 v52, v40, v56
	v_and_b32_e32 v56, 0xffff0000, v30
	v_fmac_f32_e32 v53, v41, v56
	v_lshlrev_b32_e32 v56, 16, v31
	v_fmac_f32_e32 v54, v42, v56
	v_and_b32_e32 v56, 0xffff0000, v31
	v_fmac_f32_e32 v55, v43, v56
	v_lshlrev_b32_e32 v56, 16, v32
	v_fmac_f32_e32 v52, v44, v56
	v_and_b32_e32 v56, 0xffff0000, v32
	v_fmac_f32_e32 v53, v45, v56
	v_lshlrev_b32_e32 v56, 16, v33
	v_fmac_f32_e32 v54, v46, v56
	v_and_b32_e32 v56, 0xffff0000, v33
	v_fmac_f32_e32 v55, v47, v56
	v_lshlrev_b32_e32 v56, 16, v34
	v_fmac_f32_e32 v52, v48, v56
	v_and_b32_e32 v56, 0xffff0000, v34
	v_fmac_f32_e32 v53, v49, v56
	v_lshlrev_b32_e32 v56, 16, v35
	v_fmac_f32_e32 v54, v50, v56
	v_and_b32_e32 v56, 0xffff0000, v35
	v_fmac_f32_e32 v55, v51, v56
	ds_read_b128 v[28:31], v1 offset:96
	ds_read_b128 v[32:35], v1 offset:112
	ds_read_b128 v[36:39], v3 offset:192
	ds_read_b128 v[40:43], v3 offset:208
	ds_read_b128 v[44:47], v3 offset:224
	ds_read_b128 v[48:51], v3 offset:240
	s_waitcnt lgkmcnt(6)
	v_lshlrev_b32_e32 v56, 16, v4
	v_fmac_f32_e32 v52, v12, v56
	v_and_b32_e32 v56, 0xffff0000, v4
	v_fmac_f32_e32 v53, v13, v56
	v_lshlrev_b32_e32 v56, 16, v5
	v_fmac_f32_e32 v54, v14, v56
	v_and_b32_e32 v56, 0xffff0000, v5
	v_fmac_f32_e32 v55, v15, v56
	v_lshlrev_b32_e32 v56, 16, v6
	v_fmac_f32_e32 v52, v16, v56
	v_and_b32_e32 v56, 0xffff0000, v6
	v_fmac_f32_e32 v53, v17, v56
	v_lshlrev_b32_e32 v56, 16, v7
	v_fmac_f32_e32 v54, v18, v56
	v_and_b32_e32 v56, 0xffff0000, v7
	v_fmac_f32_e32 v55, v19, v56
	v_lshlrev_b32_e32 v56, 16, v8
	v_fmac_f32_e32 v52, v20, v56
	v_and_b32_e32 v56, 0xffff0000, v8
	v_fmac_f32_e32 v53, v21, v56
	v_lshlrev_b32_e32 v56, 16, v9
	v_fmac_f32_e32 v54, v22, v56
	v_and_b32_e32 v56, 0xffff0000, v9
	v_fmac_f32_e32 v55, v23, v56
	v_lshlrev_b32_e32 v56, 16, v10
	v_fmac_f32_e32 v52, v24, v56
	v_and_b32_e32 v56, 0xffff0000, v10
	v_fmac_f32_e32 v53, v25, v56
	v_lshlrev_b32_e32 v56, 16, v11
	v_fmac_f32_e32 v54, v26, v56
	v_and_b32_e32 v56, 0xffff0000, v11
	v_fmac_f32_e32 v55, v27, v56
	ds_read_b128 v[4:7], v1 offset:128
	ds_read_b128 v[8:11], v1 offset:144
	ds_read_b128 v[12:15], v3 offset:256
	ds_read_b128 v[16:19], v3 offset:272
	ds_read_b128 v[20:23], v3 offset:288
	ds_read_b128 v[24:27], v3 offset:304
	s_waitcnt lgkmcnt(6)
	v_lshlrev_b32_e32 v56, 16, v28
	v_fmac_f32_e32 v52, v36, v56
	v_and_b32_e32 v56, 0xffff0000, v28
	v_fmac_f32_e32 v53, v37, v56
	v_lshlrev_b32_e32 v56, 16, v29
	v_fmac_f32_e32 v54, v38, v56
	v_and_b32_e32 v56, 0xffff0000, v29
	v_fmac_f32_e32 v55, v39, v56
	v_lshlrev_b32_e32 v56, 16, v30
	v_fmac_f32_e32 v52, v40, v56
	v_and_b32_e32 v56, 0xffff0000, v30
	v_fmac_f32_e32 v53, v41, v56
	v_lshlrev_b32_e32 v56, 16, v31
	v_fmac_f32_e32 v54, v42, v56
	v_and_b32_e32 v56, 0xffff0000, v31
	v_fmac_f32_e32 v55, v43, v56
	v_lshlrev_b32_e32 v56, 16, v32
	v_fmac_f32_e32 v52, v44, v56
	v_and_b32_e32 v56, 0xffff0000, v32
	v_fmac_f32_e32 v53, v45, v56
	v_lshlrev_b32_e32 v56, 16, v33
	v_fmac_f32_e32 v54, v46, v56
	v_and_b32_e32 v56, 0xffff0000, v33
	v_fmac_f32_e32 v55, v47, v56
	v_lshlrev_b32_e32 v56, 16, v34
	v_fmac_f32_e32 v52, v48, v56
	v_and_b32_e32 v56, 0xffff0000, v34
	v_fmac_f32_e32 v53, v49, v56
	v_lshlrev_b32_e32 v56, 16, v35
	v_fmac_f32_e32 v54, v50, v56
	v_and_b32_e32 v56, 0xffff0000, v35
	v_fmac_f32_e32 v55, v51, v56
	ds_read_b128 v[28:31], v1 offset:160
	ds_read_b128 v[32:35], v1 offset:176
	ds_read_b128 v[36:39], v3 offset:320
	ds_read_b128 v[40:43], v3 offset:336
	ds_read_b128 v[44:47], v3 offset:352
	ds_read_b128 v[48:51], v3 offset:368
	s_waitcnt lgkmcnt(6)
	v_lshlrev_b32_e32 v56, 16, v4
	v_fmac_f32_e32 v52, v12, v56
	v_and_b32_e32 v56, 0xffff0000, v4
	v_fmac_f32_e32 v53, v13, v56
	v_lshlrev_b32_e32 v56, 16, v5
	v_fmac_f32_e32 v54, v14, v56
	v_and_b32_e32 v56, 0xffff0000, v5
	v_fmac_f32_e32 v55, v15, v56
	v_lshlrev_b32_e32 v56, 16, v6
	v_fmac_f32_e32 v52, v16, v56
	v_and_b32_e32 v56, 0xffff0000, v6
	v_fmac_f32_e32 v53, v17, v56
	v_lshlrev_b32_e32 v56, 16, v7
	v_fmac_f32_e32 v54, v18, v56
	v_and_b32_e32 v56, 0xffff0000, v7
	v_fmac_f32_e32 v55, v19, v56
	v_lshlrev_b32_e32 v56, 16, v8
	v_fmac_f32_e32 v52, v20, v56
	v_and_b32_e32 v56, 0xffff0000, v8
	v_fmac_f32_e32 v53, v21, v56
	v_lshlrev_b32_e32 v56, 16, v9
	v_fmac_f32_e32 v54, v22, v56
	v_and_b32_e32 v56, 0xffff0000, v9
	v_fmac_f32_e32 v55, v23, v56
	v_lshlrev_b32_e32 v56, 16, v10
	v_fmac_f32_e32 v52, v24, v56
	v_and_b32_e32 v56, 0xffff0000, v10
	v_fmac_f32_e32 v53, v25, v56
	v_lshlrev_b32_e32 v56, 16, v11
	v_fmac_f32_e32 v54, v26, v56
	v_and_b32_e32 v56, 0xffff0000, v11
	v_fmac_f32_e32 v55, v27, v56
	ds_read_b128 v[4:7], v1 offset:192
	ds_read_b128 v[8:11], v1 offset:208
	ds_read_b128 v[12:15], v3 offset:384
	ds_read_b128 v[16:19], v3 offset:400
	ds_read_b128 v[20:23], v3 offset:416
	ds_read_b128 v[24:27], v3 offset:432
	s_waitcnt lgkmcnt(6)
; __device__ __forceinline__ float bf2f(bf16_t h) { return __uint_as_float(((unsigned)h) << 16); }
; __device__ __forceinline__ int sidx(int dir, int b, int h, int n) { return ((dir * 8 + b) * 4 + h) * 18 + n; }
; __device__ void ml_local_tile(unsigned char* lds, const Params& p, int l, int b, int h, int n) {
;     ...
;   if (tid < 256) {
;     const int e = tid & 127, dir = tid >> 7;
;     const float* wv = vec + (6 + dir) * 128;
;     float s = 0.f;
;     for (int q = 0; q < 128; ++q) s += wv[q] * bf2f(KT[e * 136 + q]);
;     nst[(size_t)sidx(dir, b, h, n) * 128 + e] = s;
;   }
	v_lshlrev_b32_e32 v56, 16, v28
	v_fmac_f32_e32 v52, v36, v56
	v_and_b32_e32 v56, 0xffff0000, v28
	v_fmac_f32_e32 v53, v37, v56
	v_lshlrev_b32_e32 v56, 16, v29
	v_fmac_f32_e32 v54, v38, v56
	v_and_b32_e32 v56, 0xffff0000, v29
	v_fmac_f32_e32 v55, v39, v56
	v_lshlrev_b32_e32 v56, 16, v30
	v_fmac_f32_e32 v52, v40, v56
	v_and_b32_e32 v56, 0xffff0000, v30
	v_fmac_f32_e32 v53, v41, v56
	v_lshlrev_b32_e32 v56, 16, v31
	v_fmac_f32_e32 v54, v42, v56
	v_and_b32_e32 v56, 0xffff0000, v31
	v_fmac_f32_e32 v55, v43, v56
	v_lshlrev_b32_e32 v56, 16, v32
	v_fmac_f32_e32 v52, v44, v56
	v_and_b32_e32 v56, 0xffff0000, v32
	v_fmac_f32_e32 v53, v45, v56
	v_lshlrev_b32_e32 v56, 16, v33
	v_fmac_f32_e32 v54, v46, v56
	v_and_b32_e32 v56, 0xffff0000, v33
	v_fmac_f32_e32 v55, v47, v56
	v_lshlrev_b32_e32 v56, 16, v34
	v_fmac_f32_e32 v52, v48, v56
	v_and_b32_e32 v56, 0xffff0000, v34
	v_fmac_f32_e32 v53, v49, v56
	v_lshlrev_b32_e32 v56, 16, v35
	v_fmac_f32_e32 v54, v50, v56
	v_and_b32_e32 v56, 0xffff0000, v35
	v_fmac_f32_e32 v55, v51, v56
	ds_read_b128 v[28:31], v1 offset:224
	ds_read_b128 v[32:35], v1 offset:240
	ds_read_b128 v[36:39], v3 offset:448
	ds_read_b128 v[40:43], v3 offset:464
	ds_read_b128 v[44:47], v3 offset:480
	ds_read_b128 v[48:51], v3 offset:496
	s_waitcnt lgkmcnt(6)
	v_lshlrev_b32_e32 v56, 16, v4
	v_fmac_f32_e32 v52, v12, v56
	v_and_b32_e32 v56, 0xffff0000, v4
	v_fmac_f32_e32 v53, v13, v56
	v_lshlrev_b32_e32 v56, 16, v5
	v_fmac_f32_e32 v54, v14, v56
	v_and_b32_e32 v56, 0xffff0000, v5
	v_fmac_f32_e32 v55, v15, v56
	v_lshlrev_b32_e32 v56, 16, v6
	v_fmac_f32_e32 v52, v16, v56
	v_and_b32_e32 v56, 0xffff0000, v6
	v_fmac_f32_e32 v53, v17, v56
	v_lshlrev_b32_e32 v56, 16, v7
	v_fmac_f32_e32 v54, v18, v56
	v_and_b32_e32 v56, 0xffff0000, v7
	v_fmac_f32_e32 v55, v19, v56
	v_lshlrev_b32_e32 v56, 16, v8
	v_fmac_f32_e32 v52, v20, v56
	v_and_b32_e32 v56, 0xffff0000, v8
	v_fmac_f32_e32 v53, v21, v56
	v_lshlrev_b32_e32 v56, 16, v9
	v_fmac_f32_e32 v54, v22, v56
	v_and_b32_e32 v56, 0xffff0000, v9
	v_fmac_f32_e32 v55, v23, v56
	v_lshlrev_b32_e32 v56, 16, v10
	v_fmac_f32_e32 v52, v24, v56
	v_and_b32_e32 v56, 0xffff0000, v10
	v_fmac_f32_e32 v53, v25, v56
	v_lshlrev_b32_e32 v56, 16, v11
	v_fmac_f32_e32 v54, v26, v56
	v_and_b32_e32 v56, 0xffff0000, v11
	v_fmac_f32_e32 v55, v27, v56
	s_waitcnt lgkmcnt(0)
	v_lshlrev_b32_e32 v56, 16, v28
	v_fmac_f32_e32 v52, v36, v56
	v_and_b32_e32 v56, 0xffff0000, v28
	v_fmac_f32_e32 v53, v37, v56
	v_lshlrev_b32_e32 v56, 16, v29
	v_fmac_f32_e32 v54, v38, v56
	v_and_b32_e32 v56, 0xffff0000, v29
	v_fmac_f32_e32 v55, v39, v56
	v_lshlrev_b32_e32 v56, 16, v30
	v_fmac_f32_e32 v52, v40, v56
	v_and_b32_e32 v56, 0xffff0000, v30
	v_fmac_f32_e32 v53, v41, v56
	v_lshlrev_b32_e32 v56, 16, v31
	v_fmac_f32_e32 v54, v42, v56
	v_and_b32_e32 v56, 0xffff0000, v31
	v_fmac_f32_e32 v55, v43, v56
	v_lshlrev_b32_e32 v56, 16, v32
	v_fmac_f32_e32 v52, v44, v56
	v_and_b32_e32 v56, 0xffff0000, v32
	v_fmac_f32_e32 v53, v45, v56
	v_lshlrev_b32_e32 v56, 16, v33
	v_fmac_f32_e32 v54, v46, v56
	v_and_b32_e32 v56, 0xffff0000, v33
	v_fmac_f32_e32 v55, v47, v56
	v_lshlrev_b32_e32 v56, 16, v34
	v_fmac_f32_e32 v52, v48, v56
	v_and_b32_e32 v56, 0xffff0000, v34
	v_fmac_f32_e32 v53, v49, v56
	v_lshlrev_b32_e32 v56, 16, v35
	v_fmac_f32_e32 v54, v50, v56
	v_and_b32_e32 v56, 0xffff0000, v35
	v_fmac_f32_e32 v55, v51, v56
	v_add_f32_e32 v52, v52, v53
	v_add_f32_e32 v54, v54, v55
	v_add_f32_e32 v0, v52, v54
	v_lshl_add_u32 v1, v87, 5, s2
	v_or_b32_e32 v1, s25, v1
	v_mov_b32_e32 v2, s24
	v_mad_u64_u32 v[2:3], s[2:3], v1, 18, v[2:3]
	v_ashrrev_i32_e32 v3, 31, v2
	v_readlane_b32 s2, v251, 58
	v_lshlrev_b64 v[2:3], 9, v[2:3]
	v_readlane_b32 s3, v251, 59
	v_lshlrev_b32_e32 v192, 2, v86
	s_nop 0
	v_lshl_add_u64 v[2:3], s[2:3], 0, v[2:3]
	v_lshl_add_u64 v[2:3], v[2:3], 0, v[192:193]
	global_store_dword v[2:3], v0, off
	s_branch .LBB0_321
